# gate/up GEMM: hand-written epilogue for both tiles of a pair straight from their accumulators (no second setup pass, no register shuffles); loads for rstd batched
# speedup vs baseline: 1.2985x; 1.0149x over previous
; template <class F>
; DEVINL void gemm_phase(int NT, F&& f) {
;     ...
;   const int x = bid & 7, j = bid >> 3, nbx = nb >> 3;
;   const int u0 = (int)(((long)U * x) >> 3), u1 = (int)(((long)U * (x + 1)) >> 3);
;   for (int u = u0 + j; u < u1; u += nbx) {
;     const int band = u / (8 * MT), v = u - band * 8 * MT;
;     const int w = min(8, NT - band * 8);
;     f(v / w, band * 8 + v % w);
.LBB0_112:
	s_andn2_saveexec_b64 s[34:35], s[34:35]
	s_cbranch_execz .LBB0_119
	s_and_b32 s1, s0, 7
	s_ashr_i32 s36, s0, 3
	s_mul_i32 s0, s1, 0xbc6
	s_lshr_b32 s1, s0, 3
	s_addk_i32 s0, 0xbc6
	s_lshr_b32 s0, s0, 3
	s_add_i32 s1, s1, s36
	s_lshl_b32 s1, s1, 1
	s_lshl_b32 s0, s0, 1
	s_cmp_ge_i32 s1, s0
	s_cbranch_scc1 .LBB0_119
	v_ashrrev_i32_e32 v1, 2, v104
	s_mov_b64 s[36:37], 0
	v_mov_b32_e32 v3, s1

; DEVINL int tidx() { int t = threadIdx.x; asm volatile("" : "+v"(t)); return t; }
; DEVINL void gemm_loop(f32x4 (&acc)[4][4], const u16* __restrict__ A, int lda, const u16* __restrict__ Bt, int ldb,
;                       int m0, int n0, int k0, int nk, char* smem) {
;   const int tid = tidx(), wid = tid >> 6, lane = tid & 63;
;   const int wr = wid >> 1, wc = wid & 1;
;   const u16* ga[4]; const u16* gb[4];
; #pragma unroll
;   for (int i = 0; i < 4; ++i) {
;     int s = i * 256 + tid, r = s >> 3, c = (s & 7) ^ ((r >> 1) & 7);
;     ga[i] = A + (size_t)(m0 + r) * lda + k0 + c * 8;
;     gb[i] = Bt + (size_t)(n0 + r) * ldb + k0 + c * 8;
;   }
;   const int fr = lane & 15, fq = lane >> 4;
;   __syncthreads();
; #pragma unroll
;   for (int i = 0; i < 4; ++i) {
;     glds16(ga[i], smem + i * 4096 + wid * 1024);
;     glds16(gb[i], smem + 16384 + i * 4096 + wid * 1024);
;   }
.LBB0_116:
	v_writelane_b32 v195, s52, 0
	v_writelane_b32 v195, s53, 1
	v_writelane_b32 v195, s54, 2
	v_writelane_b32 v195, s55, 3
	v_writelane_b32 v195, s56, 4
	v_writelane_b32 v195, s57, 5
	v_writelane_b32 v195, s58, 6
	v_writelane_b32 v195, s59, 7
	v_readfirstlane_b32 s40, v84
	v_mov_b32_e32 v188, 0
	v_mov_b32_e32 v189, 0
	v_mov_b32_e32 v190, 0
	v_mov_b32_e32 v191, 0
	v_mov_b32_e32 v196, 0
	v_mov_b32_e32 v197, 0
	v_mov_b32_e32 v198, 0
	v_mov_b32_e32 v199, 0
	v_mov_b32_e32 v200, 0
	v_mov_b32_e32 v201, 0
	v_mov_b32_e32 v202, 0
	v_mov_b32_e32 v203, 0
	v_mov_b32_e32 v204, 0
	v_mov_b32_e32 v205, 0
	v_mov_b32_e32 v206, 0
	v_mov_b32_e32 v207, 0
	v_mov_b32_e32 v208, 0
	v_mov_b32_e32 v209, 0
	v_mov_b32_e32 v210, 0
	v_mov_b32_e32 v211, 0
	v_mov_b32_e32 v212, 0
	v_mov_b32_e32 v213, 0
	v_mov_b32_e32 v214, 0
	v_mov_b32_e32 v215, 0
	v_mov_b32_e32 v216, 0
	v_mov_b32_e32 v217, 0
	v_mov_b32_e32 v218, 0
	v_mov_b32_e32 v219, 0
	v_mov_b32_e32 v220, 0
	v_mov_b32_e32 v221, 0
	v_mov_b32_e32 v222, 0
	v_mov_b32_e32 v223, 0
	v_mov_b32_e32 v224, 0
	v_mov_b32_e32 v225, 0
	v_mov_b32_e32 v226, 0
	v_mov_b32_e32 v227, 0
	v_mov_b32_e32 v228, 0
	v_mov_b32_e32 v229, 0
	v_mov_b32_e32 v230, 0
	v_mov_b32_e32 v231, 0
	v_mov_b32_e32 v232, 0
	v_mov_b32_e32 v233, 0
	v_mov_b32_e32 v234, 0
	v_mov_b32_e32 v235, 0
	v_mov_b32_e32 v236, 0
	v_mov_b32_e32 v237, 0
	v_mov_b32_e32 v238, 0
	v_mov_b32_e32 v239, 0
	v_mov_b32_e32 v240, 0
	v_mov_b32_e32 v241, 0
	v_mov_b32_e32 v242, 0
	v_mov_b32_e32 v243, 0
	v_mov_b32_e32 v244, 0
	v_mov_b32_e32 v245, 0
	v_mov_b32_e32 v246, 0
	v_mov_b32_e32 v247, 0
	v_mov_b32_e32 v248, 0
	v_mov_b32_e32 v249, 0
	v_mov_b32_e32 v250, 0
	v_mov_b32_e32 v251, 0
	v_mov_b32_e32 v252, 0
	v_mov_b32_e32 v253, 0
	v_mov_b32_e32 v254, 0
	v_mov_b32_e32 v255, 0
	s_mov_b32 s52, 0x0
	s_mov_b32 s53, 0x4000
	s_mov_b32 s54, 0x8000
	s_mov_b32 s55, 0xc000
	s_mov_b32 s56, 0x10000
	s_mov_b32 s58, 0xffffff80
	s_mov_b32 s59, -1
	s_mov_b32 s38, 0x3ff80
	s_mov_b32 s39, 0
	s_add_u32 s41, s52, s40
	s_add_u32 m0, s41, 0x0
	v_lshl_add_u64 v[122:123], v[4:5], 0, s[58:59]
	global_load_lds_dwordx4 v[122:123], off
	s_add_u32 m0, s41, 0x1000
	v_lshl_add_u64 v[122:123], v[8:9], 0, s[58:59]
	global_load_lds_dwordx4 v[122:123], off
	s_add_u32 m0, s41, 0x2000
	v_lshl_add_u64 v[122:123], v[16:17], 0, s[58:59]
	global_load_lds_dwordx4 v[122:123], off
	s_add_u32 m0, s41, 0x3000
	v_lshl_add_u64 v[122:123], v[80:81], 0, s[58:59]
	global_load_lds_dwordx4 v[122:123], off
	s_add_u32 s41, s53, s40
	s_add_u32 m0, s41, 0x0
	v_lshl_add_u64 v[122:123], v[6:7], 0, s[58:59]
	global_load_lds_dwordx4 v[122:123], off
	s_add_u32 m0, s41, 0x1000
	v_lshl_add_u64 v[122:123], v[10:11], 0, s[58:59]
	global_load_lds_dwordx4 v[122:123], off
	s_add_u32 m0, s41, 0x2000
	v_lshl_add_u64 v[122:123], v[18:19], 0, s[58:59]
	global_load_lds_dwordx4 v[122:123], off
	s_add_u32 m0, s41, 0x3000
	v_lshl_add_u64 v[122:123], v[82:83], 0, s[58:59]
	global_load_lds_dwordx4 v[122:123], off
	s_add_u32 s41, s54, s40
	s_add_u32 m0, s41, 0x0
	v_lshl_add_u64 v[122:123], v[6:7], 0, s[38:39]
	global_load_lds_dwordx4 v[122:123], off
	s_add_u32 m0, s41, 0x1000
	v_lshl_add_u64 v[122:123], v[10:11], 0, s[38:39]
	global_load_lds_dwordx4 v[122:123], off
	s_add_u32 m0, s41, 0x2000
	v_lshl_add_u64 v[122:123], v[18:19], 0, s[38:39]
	global_load_lds_dwordx4 v[122:123], off
	s_add_u32 m0, s41, 0x3000
	v_lshl_add_u64 v[122:123], v[82:83], 0, s[38:39]
	global_load_lds_dwordx4 v[122:123], off
	s_mov_b64 s[58:59], 0
	s_add_u32 s41, s55, s40
	s_add_u32 m0, s41, 0x0
	v_lshl_add_u64 v[122:123], v[4:5], 0, s[58:59]
	global_load_lds_dwordx4 v[122:123], off
	s_add_u32 m0, s41, 0x1000
	v_lshl_add_u64 v[122:123], v[8:9], 0, s[58:59]
	global_load_lds_dwordx4 v[122:123], off
	s_add_u32 m0, s41, 0x2000
	v_lshl_add_u64 v[122:123], v[16:17], 0, s[58:59]
	global_load_lds_dwordx4 v[122:123], off
	s_add_u32 m0, s41, 0x3000
	v_lshl_add_u64 v[122:123], v[80:81], 0, s[58:59]
	global_load_lds_dwordx4 v[122:123], off
	s_add_u32 s41, s56, s40
	s_add_u32 m0, s41, 0x0
	v_lshl_add_u64 v[122:123], v[6:7], 0, s[58:59]
	global_load_lds_dwordx4 v[122:123], off
	s_add_u32 m0, s41, 0x1000
	v_lshl_add_u64 v[122:123], v[10:11], 0, s[58:59]
	global_load_lds_dwordx4 v[122:123], off
	s_add_u32 m0, s41, 0x2000
	v_lshl_add_u64 v[122:123], v[18:19], 0, s[58:59]
	global_load_lds_dwordx4 v[122:123], off
	s_add_u32 m0, s41, 0x3000
	v_lshl_add_u64 v[122:123], v[82:83], 0, s[58:59]
	global_load_lds_dwordx4 v[122:123], off
	s_mov_b32 s38, 0x40000
	s_mov_b32 s58, 0x80
	s_mov_b32 s1, 14
	s_waitcnt vmcnt(12)
	s_barrier
	v_add3_u32 v124, v85, v88, s52
	v_add3_u32 v125, v86, v88, s53
	ds_read_b128 v[106:109], v124
	ds_read_b128 v[110:113], v124 offset:2048
	ds_read_b128 v[140:143], v124 offset:4096
	ds_read_b128 v[144:147], v124 offset:6144
	ds_read_b128 v[132:135], v125
	ds_read_b128 v[136:139], v125 offset:2048
	ds_read_b128 v[148:151], v125 offset:4096
	ds_read_b128 v[152:155], v125 offset:6144
; DEVINL f32x4 mfma16(bf16x8 a, bf16x8 b, f32x4 c) { return __builtin_amdgcn_mfma_f32_16x16x32_bf16(a, b, c, 0, 0, 0); }
; DEVINL void gemm_loop(f32x4 (&acc)[4][4], const u16* __restrict__ A, int lda, const u16* __restrict__ Bt, int ldb,
;                       int m0, int n0, int k0, int nk, char* smem) {
;     ...
;   for (int kt = 0; kt < nk; ++kt) {
;     __syncthreads();
;     char* cur = smem + (kt & 1) * 32768;
;     if (kt + 1 < nk) {
;       char* nxt = smem + ((kt + 1) & 1) * 32768;
; #pragma unroll
;       for (int i = 0; i < 4; ++i) {
;         glds16(ga[i] + (kt + 1) * 64, nxt + i * 4096 + wid * 1024);
;         glds16(gb[i] + (kt + 1) * 64, nxt + 16384 + i * 4096 + wid * 1024);
;       }
;     }
;     bf16x8 af[2][4], bfr[2][4];
; #pragma unroll
;     for (int ks = 0; ks < 2; ++ks)
; #pragma unroll
;       for (int f = 0; f < 4; ++f) {
;         int ra = wr * 64 + f * 16 + fr, rb = wc * 64 + f * 16 + fr;
;         int ch = ks * 4 + fq;
;         af[ks][f] = *(const bf16x8*)(cur + ra * 128 + ((ch ^ ((ra >> 1) & 7)) << 4));
;         bfr[ks][f] = *(const bf16x8*)(cur + 16384 + rb * 128 + ((ch ^ ((rb >> 1) & 7)) << 4));
;       }
;     __builtin_amdgcn_sched_barrier(0);
; #pragma unroll
;     for (int ks = 0; ks < 2; ++ks)
; #pragma unroll
;       for (int mf = 0; mf < 4; ++mf)
; #pragma unroll
;         for (int nf = 0; nf < 4; ++nf) acc[mf][nf] = mfma16(af[ks][mf], bfr[ks][nf], acc[mf][nf]);
.Ldt_b116_loop:
	v_add3_u32 v124, v85, v87, s52
	v_add3_u32 v125, v86, v87, s53
	ds_read_b128 v[156:159], v124
	ds_read_b128 v[160:163], v124 offset:2048
	ds_read_b128 v[172:175], v124 offset:4096
	ds_read_b128 v[176:179], v124 offset:6144
	ds_read_b128 v[164:167], v125
	ds_read_b128 v[168:171], v125 offset:2048
	ds_read_b128 v[180:183], v125 offset:4096
	ds_read_b128 v[184:187], v125 offset:6144
	s_waitcnt lgkmcnt(8)
	v_mfma_f32_16x16x32_bf16 v[76:79], v[106:109], v[132:135], v[76:79]
	v_mfma_f32_16x16x32_bf16 v[72:75], v[106:109], v[136:139], v[72:75]
	v_mfma_f32_16x16x32_bf16 v[68:71], v[106:109], v[148:151], v[68:71]
	v_mfma_f32_16x16x32_bf16 v[64:67], v[106:109], v[152:155], v[64:67]
	v_mfma_f32_16x16x32_bf16 v[60:63], v[110:113], v[132:135], v[60:63]
	v_mfma_f32_16x16x32_bf16 v[56:59], v[110:113], v[136:139], v[56:59]
	v_mfma_f32_16x16x32_bf16 v[52:55], v[110:113], v[148:151], v[52:55]
	v_mfma_f32_16x16x32_bf16 v[48:51], v[110:113], v[152:155], v[48:51]
	v_mfma_f32_16x16x32_bf16 v[44:47], v[140:143], v[132:135], v[44:47]
	v_mfma_f32_16x16x32_bf16 v[40:43], v[140:143], v[136:139], v[40:43]
	v_mfma_f32_16x16x32_bf16 v[36:39], v[140:143], v[148:151], v[36:39]
	v_mfma_f32_16x16x32_bf16 v[28:31], v[140:143], v[152:155], v[28:31]
	v_mfma_f32_16x16x32_bf16 v[24:27], v[144:147], v[132:135], v[24:27]
	v_mfma_f32_16x16x32_bf16 v[20:23], v[144:147], v[136:139], v[20:23]
	v_mfma_f32_16x16x32_bf16 v[12:15], v[144:147], v[148:151], v[12:15]
	v_mfma_f32_16x16x32_bf16 v[32:35], v[144:147], v[152:155], v[32:35]
	s_waitcnt vmcnt(8) lgkmcnt(0)
	s_barrier
	s_add_u32 s41, s52, s40
	s_add_u32 m0, s41, 0x0
	v_lshl_add_u64 v[122:123], v[6:7], 0, s[38:39]
	global_load_lds_dwordx4 v[122:123], off
	s_add_u32 m0, s41, 0x1000
	v_lshl_add_u64 v[122:123], v[10:11], 0, s[38:39]
	global_load_lds_dwordx4 v[122:123], off
	s_add_u32 m0, s41, 0x2000
	v_lshl_add_u64 v[122:123], v[18:19], 0, s[38:39]
	global_load_lds_dwordx4 v[122:123], off
	s_add_u32 m0, s41, 0x3000
	v_lshl_add_u64 v[122:123], v[82:83], 0, s[38:39]
	global_load_lds_dwordx4 v[122:123], off
	s_add_u32 s41, s53, s40
	s_add_u32 m0, s41, 0x0
	v_lshl_add_u64 v[122:123], v[4:5], 0, s[58:59]
	global_load_lds_dwordx4 v[122:123], off
	s_add_u32 m0, s41, 0x1000
	v_lshl_add_u64 v[122:123], v[8:9], 0, s[58:59]
	global_load_lds_dwordx4 v[122:123], off
	s_add_u32 m0, s41, 0x2000
	v_lshl_add_u64 v[122:123], v[16:17], 0, s[58:59]
	global_load_lds_dwordx4 v[122:123], off
	s_add_u32 m0, s41, 0x3000
	v_lshl_add_u64 v[122:123], v[80:81], 0, s[58:59]
	global_load_lds_dwordx4 v[122:123], off
	v_add3_u32 v125, v86, v88, s54
	ds_read_b128 v[132:135], v125
	ds_read_b128 v[136:139], v125 offset:2048
	ds_read_b128 v[148:151], v125 offset:4096
	ds_read_b128 v[152:155], v125 offset:6144
	v_mfma_f32_16x16x32_bf16 v[76:79], v[156:159], v[164:167], v[76:79]
	v_mfma_f32_16x16x32_bf16 v[72:75], v[156:159], v[168:171], v[72:75]
	v_mfma_f32_16x16x32_bf16 v[68:71], v[156:159], v[180:183], v[68:71]
	v_mfma_f32_16x16x32_bf16 v[64:67], v[156:159], v[184:187], v[64:67]
	v_mfma_f32_16x16x32_bf16 v[60:63], v[160:163], v[164:167], v[60:63]
	v_mfma_f32_16x16x32_bf16 v[56:59], v[160:163], v[168:171], v[56:59]
	v_mfma_f32_16x16x32_bf16 v[52:55], v[160:163], v[180:183], v[52:55]
	v_mfma_f32_16x16x32_bf16 v[48:51], v[160:163], v[184:187], v[48:51]
	v_mfma_f32_16x16x32_bf16 v[44:47], v[172:175], v[164:167], v[44:47]
	v_mfma_f32_16x16x32_bf16 v[40:43], v[172:175], v[168:171], v[40:43]
	v_mfma_f32_16x16x32_bf16 v[36:39], v[172:175], v[180:183], v[36:39]
	v_mfma_f32_16x16x32_bf16 v[28:31], v[172:175], v[184:187], v[28:31]
	v_mfma_f32_16x16x32_bf16 v[24:27], v[176:179], v[164:167], v[24:27]
	v_mfma_f32_16x16x32_bf16 v[20:23], v[176:179], v[168:171], v[20:23]
	v_mfma_f32_16x16x32_bf16 v[12:15], v[176:179], v[180:183], v[12:15]
	v_mfma_f32_16x16x32_bf16 v[32:35], v[176:179], v[184:187], v[32:35]
	s_waitcnt lgkmcnt(0)
	v_add3_u32 v125, v86, v87, s54
	ds_read_b128 v[164:167], v125
	ds_read_b128 v[168:171], v125 offset:2048
	ds_read_b128 v[180:183], v125 offset:4096
	ds_read_b128 v[184:187], v125 offset:6144
	v_mfma_f32_16x16x32_bf16 v[188:191], v[106:109], v[132:135], v[188:191]
	v_mfma_f32_16x16x32_bf16 v[196:199], v[106:109], v[136:139], v[196:199]
	v_mfma_f32_16x16x32_bf16 v[200:203], v[106:109], v[148:151], v[200:203]
	v_mfma_f32_16x16x32_bf16 v[204:207], v[106:109], v[152:155], v[204:207]
	v_mfma_f32_16x16x32_bf16 v[208:211], v[110:113], v[132:135], v[208:211]
	v_mfma_f32_16x16x32_bf16 v[212:215], v[110:113], v[136:139], v[212:215]
	v_mfma_f32_16x16x32_bf16 v[216:219], v[110:113], v[148:151], v[216:219]
	v_mfma_f32_16x16x32_bf16 v[220:223], v[110:113], v[152:155], v[220:223]
	v_mfma_f32_16x16x32_bf16 v[224:227], v[140:143], v[132:135], v[224:227]
	v_mfma_f32_16x16x32_bf16 v[228:231], v[140:143], v[136:139], v[228:231]
	v_mfma_f32_16x16x32_bf16 v[232:235], v[140:143], v[148:151], v[232:235]
	v_mfma_f32_16x16x32_bf16 v[236:239], v[140:143], v[152:155], v[236:239]
	v_mfma_f32_16x16x32_bf16 v[240:243], v[144:147], v[132:135], v[240:243]
	v_mfma_f32_16x16x32_bf16 v[244:247], v[144:147], v[136:139], v[244:247]
	v_mfma_f32_16x16x32_bf16 v[248:251], v[144:147], v[148:151], v[248:251]
	v_mfma_f32_16x16x32_bf16 v[252:255], v[144:147], v[152:155], v[252:255]
	s_waitcnt vmcnt(8) lgkmcnt(0)
	s_barrier
; DEVINL f32x4 mfma16(bf16x8 a, bf16x8 b, f32x4 c) { return __builtin_amdgcn_mfma_f32_16x16x32_bf16(a, b, c, 0, 0, 0); }
; DEVINL void gemm_loop(f32x4 (&acc)[4][4], const u16* __restrict__ A, int lda, const u16* __restrict__ Bt, int ldb,
;                       int m0, int n0, int k0, int nk, char* smem) {
;     ...
;   for (int kt = 0; kt < nk; ++kt) {
;     __syncthreads();
;     char* cur = smem + (kt & 1) * 32768;
;     if (kt + 1 < nk) {
;       char* nxt = smem + ((kt + 1) & 1) * 32768;
; #pragma unroll
;       for (int i = 0; i < 4; ++i) {
;         glds16(ga[i] + (kt + 1) * 64, nxt + i * 4096 + wid * 1024);
;         glds16(gb[i] + (kt + 1) * 64, nxt + 16384 + i * 4096 + wid * 1024);
;       }
;     }
;     bf16x8 af[2][4], bfr[2][4];
; #pragma unroll
;     for (int ks = 0; ks < 2; ++ks)
; #pragma unroll
;       for (int f = 0; f < 4; ++f) {
;         int ra = wr * 64 + f * 16 + fr, rb = wc * 64 + f * 16 + fr;
;         int ch = ks * 4 + fq;
;         af[ks][f] = *(const bf16x8*)(cur + ra * 128 + ((ch ^ ((ra >> 1) & 7)) << 4));
;         bfr[ks][f] = *(const bf16x8*)(cur + 16384 + rb * 128 + ((ch ^ ((rb >> 1) & 7)) << 4));
;       }
;     __builtin_amdgcn_sched_barrier(0);
; #pragma unroll
;     for (int ks = 0; ks < 2; ++ks)
; #pragma unroll
;       for (int mf = 0; mf < 4; ++mf)
; #pragma unroll
;         for (int nf = 0; nf < 4; ++nf) acc[mf][nf] = mfma16(af[ks][mf], bfr[ks][nf], acc[mf][nf]);
	s_add_u32 s41, s54, s40
	s_add_u32 m0, s41, 0x0
	v_lshl_add_u64 v[122:123], v[6:7], 0, s[58:59]
	global_load_lds_dwordx4 v[122:123], off
	s_add_u32 m0, s41, 0x1000
	v_lshl_add_u64 v[122:123], v[10:11], 0, s[58:59]
	global_load_lds_dwordx4 v[122:123], off
	s_add_u32 m0, s41, 0x2000
	v_lshl_add_u64 v[122:123], v[18:19], 0, s[58:59]
	global_load_lds_dwordx4 v[122:123], off
	s_add_u32 m0, s41, 0x3000
	v_lshl_add_u64 v[122:123], v[82:83], 0, s[58:59]
	global_load_lds_dwordx4 v[122:123], off
	v_add3_u32 v124, v85, v88, s55
	v_add3_u32 v125, v86, v88, s56
	ds_read_b128 v[106:109], v124
	ds_read_b128 v[110:113], v124 offset:2048
	ds_read_b128 v[140:143], v124 offset:4096
	ds_read_b128 v[144:147], v124 offset:6144
	ds_read_b128 v[132:135], v125
	ds_read_b128 v[136:139], v125 offset:2048
	ds_read_b128 v[148:151], v125 offset:4096
	ds_read_b128 v[152:155], v125 offset:6144
	v_mfma_f32_16x16x32_bf16 v[188:191], v[156:159], v[164:167], v[188:191]
	v_mfma_f32_16x16x32_bf16 v[196:199], v[156:159], v[168:171], v[196:199]
	v_mfma_f32_16x16x32_bf16 v[200:203], v[156:159], v[180:183], v[200:203]
	v_mfma_f32_16x16x32_bf16 v[204:207], v[156:159], v[184:187], v[204:207]
	v_mfma_f32_16x16x32_bf16 v[208:211], v[160:163], v[164:167], v[208:211]
	v_mfma_f32_16x16x32_bf16 v[212:215], v[160:163], v[168:171], v[212:215]
	v_mfma_f32_16x16x32_bf16 v[216:219], v[160:163], v[180:183], v[216:219]
	v_mfma_f32_16x16x32_bf16 v[220:223], v[160:163], v[184:187], v[220:223]
	v_mfma_f32_16x16x32_bf16 v[224:227], v[172:175], v[164:167], v[224:227]
	v_mfma_f32_16x16x32_bf16 v[228:231], v[172:175], v[168:171], v[228:231]
	v_mfma_f32_16x16x32_bf16 v[232:235], v[172:175], v[180:183], v[232:235]
	v_mfma_f32_16x16x32_bf16 v[236:239], v[172:175], v[184:187], v[236:239]
	v_mfma_f32_16x16x32_bf16 v[240:243], v[176:179], v[164:167], v[240:243]
	v_mfma_f32_16x16x32_bf16 v[244:247], v[176:179], v[168:171], v[244:247]
	v_mfma_f32_16x16x32_bf16 v[248:251], v[176:179], v[180:183], v[248:251]
	v_mfma_f32_16x16x32_bf16 v[252:255], v[176:179], v[184:187], v[252:255]
	s_mov_b32 s41, s52
	s_mov_b32 s100, s53
	s_mov_b32 s52, s55
	s_mov_b32 s53, s56
	s_mov_b32 s55, s100
	s_mov_b32 s100, s54
	s_mov_b32 s54, s41
	s_mov_b32 s56, s100
	s_add_u32 s38, s38, 0x80
	s_addc_u32 s39, s39, 0
	s_add_u32 s58, s58, 0x80
	s_addc_u32 s59, s59, 0
	s_sub_u32 s1, s1, 1
	s_cmp_lg_u32 s1, 0
	s_cbranch_scc1 .Ldt_b116_loop
	v_add3_u32 v124, v85, v87, s52
	v_add3_u32 v125, v86, v87, s53
	ds_read_b128 v[156:159], v124
	ds_read_b128 v[160:163], v124 offset:2048
	ds_read_b128 v[172:175], v124 offset:4096
	ds_read_b128 v[176:179], v124 offset:6144
	ds_read_b128 v[164:167], v125
	ds_read_b128 v[168:171], v125 offset:2048
	ds_read_b128 v[180:183], v125 offset:4096
	ds_read_b128 v[184:187], v125 offset:6144
	s_waitcnt lgkmcnt(8)
	v_mfma_f32_16x16x32_bf16 v[76:79], v[106:109], v[132:135], v[76:79]
	v_mfma_f32_16x16x32_bf16 v[72:75], v[106:109], v[136:139], v[72:75]
	v_mfma_f32_16x16x32_bf16 v[68:71], v[106:109], v[148:151], v[68:71]
	v_mfma_f32_16x16x32_bf16 v[64:67], v[106:109], v[152:155], v[64:67]
	v_mfma_f32_16x16x32_bf16 v[60:63], v[110:113], v[132:135], v[60:63]
	v_mfma_f32_16x16x32_bf16 v[56:59], v[110:113], v[136:139], v[56:59]
	v_mfma_f32_16x16x32_bf16 v[52:55], v[110:113], v[148:151], v[52:55]
	v_mfma_f32_16x16x32_bf16 v[48:51], v[110:113], v[152:155], v[48:51]
	v_mfma_f32_16x16x32_bf16 v[44:47], v[140:143], v[132:135], v[44:47]
	v_mfma_f32_16x16x32_bf16 v[40:43], v[140:143], v[136:139], v[40:43]
	v_mfma_f32_16x16x32_bf16 v[36:39], v[140:143], v[148:151], v[36:39]
	v_mfma_f32_16x16x32_bf16 v[28:31], v[140:143], v[152:155], v[28:31]
	v_mfma_f32_16x16x32_bf16 v[24:27], v[144:147], v[132:135], v[24:27]
	v_mfma_f32_16x16x32_bf16 v[20:23], v[144:147], v[136:139], v[20:23]
	v_mfma_f32_16x16x32_bf16 v[12:15], v[144:147], v[148:151], v[12:15]
	v_mfma_f32_16x16x32_bf16 v[32:35], v[144:147], v[152:155], v[32:35]
	s_waitcnt vmcnt(8) lgkmcnt(0)
	s_barrier
	s_add_u32 s41, s52, s40
	s_add_u32 m0, s41, 0x0
	v_lshl_add_u64 v[122:123], v[6:7], 0, s[38:39]
	global_load_lds_dwordx4 v[122:123], off
	s_add_u32 m0, s41, 0x1000
	v_lshl_add_u64 v[122:123], v[10:11], 0, s[38:39]
	global_load_lds_dwordx4 v[122:123], off
	s_add_u32 m0, s41, 0x2000
	v_lshl_add_u64 v[122:123], v[18:19], 0, s[38:39]
	global_load_lds_dwordx4 v[122:123], off
	s_add_u32 m0, s41, 0x3000
	v_lshl_add_u64 v[122:123], v[82:83], 0, s[38:39]
	global_load_lds_dwordx4 v[122:123], off
	v_add3_u32 v125, v86, v88, s54
	ds_read_b128 v[132:135], v125
	ds_read_b128 v[136:139], v125 offset:2048
	ds_read_b128 v[148:151], v125 offset:4096
	ds_read_b128 v[152:155], v125 offset:6144
	v_mfma_f32_16x16x32_bf16 v[76:79], v[156:159], v[164:167], v[76:79]
	v_mfma_f32_16x16x32_bf16 v[72:75], v[156:159], v[168:171], v[72:75]
	v_mfma_f32_16x16x32_bf16 v[68:71], v[156:159], v[180:183], v[68:71]
	v_mfma_f32_16x16x32_bf16 v[64:67], v[156:159], v[184:187], v[64:67]
	v_mfma_f32_16x16x32_bf16 v[60:63], v[160:163], v[164:167], v[60:63]
	v_mfma_f32_16x16x32_bf16 v[56:59], v[160:163], v[168:171], v[56:59]
	v_mfma_f32_16x16x32_bf16 v[52:55], v[160:163], v[180:183], v[52:55]
	v_mfma_f32_16x16x32_bf16 v[48:51], v[160:163], v[184:187], v[48:51]
	v_mfma_f32_16x16x32_bf16 v[44:47], v[172:175], v[164:167], v[44:47]
	v_mfma_f32_16x16x32_bf16 v[40:43], v[172:175], v[168:171], v[40:43]
	v_mfma_f32_16x16x32_bf16 v[36:39], v[172:175], v[180:183], v[36:39]
	v_mfma_f32_16x16x32_bf16 v[28:31], v[172:175], v[184:187], v[28:31]
	v_mfma_f32_16x16x32_bf16 v[24:27], v[176:179], v[164:167], v[24:27]
	v_mfma_f32_16x16x32_bf16 v[20:23], v[176:179], v[168:171], v[20:23]
	v_mfma_f32_16x16x32_bf16 v[12:15], v[176:179], v[180:183], v[12:15]
	v_mfma_f32_16x16x32_bf16 v[32:35], v[176:179], v[184:187], v[32:35]
	s_waitcnt lgkmcnt(0)
; DEVINL f32x4 mfma16(bf16x8 a, bf16x8 b, f32x4 c) { return __builtin_amdgcn_mfma_f32_16x16x32_bf16(a, b, c, 0, 0, 0); }
; DEVINL void gemm_loop(f32x4 (&acc)[4][4], const u16* __restrict__ A, int lda, const u16* __restrict__ Bt, int ldb,
;                       int m0, int n0, int k0, int nk, char* smem) {
;     ...
;   for (int kt = 0; kt < nk; ++kt) {
;     __syncthreads();
;     char* cur = smem + (kt & 1) * 32768;
;     if (kt + 1 < nk) {
;       char* nxt = smem + ((kt + 1) & 1) * 32768;
; #pragma unroll
;       for (int i = 0; i < 4; ++i) {
;         glds16(ga[i] + (kt + 1) * 64, nxt + i * 4096 + wid * 1024);
;         glds16(gb[i] + (kt + 1) * 64, nxt + 16384 + i * 4096 + wid * 1024);
;       }
;     }
;     bf16x8 af[2][4], bfr[2][4];
; #pragma unroll
;     for (int ks = 0; ks < 2; ++ks)
; #pragma unroll
;       for (int f = 0; f < 4; ++f) {
;         int ra = wr * 64 + f * 16 + fr, rb = wc * 64 + f * 16 + fr;
;         int ch = ks * 4 + fq;
;         af[ks][f] = *(const bf16x8*)(cur + ra * 128 + ((ch ^ ((ra >> 1) & 7)) << 4));
;         bfr[ks][f] = *(const bf16x8*)(cur + 16384 + rb * 128 + ((ch ^ ((rb >> 1) & 7)) << 4));
;       }
;     __builtin_amdgcn_sched_barrier(0);
; #pragma unroll
;     for (int ks = 0; ks < 2; ++ks)
; #pragma unroll
;       for (int mf = 0; mf < 4; ++mf)
; #pragma unroll
;         for (int nf = 0; nf < 4; ++nf) acc[mf][nf] = mfma16(af[ks][mf], bfr[ks][nf], acc[mf][nf]);
	v_add3_u32 v125, v86, v87, s54
	ds_read_b128 v[164:167], v125
	ds_read_b128 v[168:171], v125 offset:2048
	ds_read_b128 v[180:183], v125 offset:4096
	ds_read_b128 v[184:187], v125 offset:6144
	v_mfma_f32_16x16x32_bf16 v[188:191], v[106:109], v[132:135], v[188:191]
	v_mfma_f32_16x16x32_bf16 v[196:199], v[106:109], v[136:139], v[196:199]
	v_mfma_f32_16x16x32_bf16 v[200:203], v[106:109], v[148:151], v[200:203]
	v_mfma_f32_16x16x32_bf16 v[204:207], v[106:109], v[152:155], v[204:207]
	v_mfma_f32_16x16x32_bf16 v[208:211], v[110:113], v[132:135], v[208:211]
	v_mfma_f32_16x16x32_bf16 v[212:215], v[110:113], v[136:139], v[212:215]
	v_mfma_f32_16x16x32_bf16 v[216:219], v[110:113], v[148:151], v[216:219]
	v_mfma_f32_16x16x32_bf16 v[220:223], v[110:113], v[152:155], v[220:223]
	v_mfma_f32_16x16x32_bf16 v[224:227], v[140:143], v[132:135], v[224:227]
	v_mfma_f32_16x16x32_bf16 v[228:231], v[140:143], v[136:139], v[228:231]
	v_mfma_f32_16x16x32_bf16 v[232:235], v[140:143], v[148:151], v[232:235]
	v_mfma_f32_16x16x32_bf16 v[236:239], v[140:143], v[152:155], v[236:239]
	v_mfma_f32_16x16x32_bf16 v[240:243], v[144:147], v[132:135], v[240:243]
	v_mfma_f32_16x16x32_bf16 v[244:247], v[144:147], v[136:139], v[244:247]
	v_mfma_f32_16x16x32_bf16 v[248:251], v[144:147], v[148:151], v[248:251]
	v_mfma_f32_16x16x32_bf16 v[252:255], v[144:147], v[152:155], v[252:255]
	s_waitcnt vmcnt(4) lgkmcnt(0)
	s_barrier
	v_add3_u32 v124, v85, v88, s55
	v_add3_u32 v125, v86, v88, s56
	ds_read_b128 v[106:109], v124
	ds_read_b128 v[110:113], v124 offset:2048
	ds_read_b128 v[140:143], v124 offset:4096
	ds_read_b128 v[144:147], v124 offset:6144
	ds_read_b128 v[132:135], v125
	ds_read_b128 v[136:139], v125 offset:2048
	ds_read_b128 v[148:151], v125 offset:4096
	ds_read_b128 v[152:155], v125 offset:6144
	v_mfma_f32_16x16x32_bf16 v[188:191], v[156:159], v[164:167], v[188:191]
	v_mfma_f32_16x16x32_bf16 v[196:199], v[156:159], v[168:171], v[196:199]
	v_mfma_f32_16x16x32_bf16 v[200:203], v[156:159], v[180:183], v[200:203]
	v_mfma_f32_16x16x32_bf16 v[204:207], v[156:159], v[184:187], v[204:207]
	v_mfma_f32_16x16x32_bf16 v[208:211], v[160:163], v[164:167], v[208:211]
	v_mfma_f32_16x16x32_bf16 v[212:215], v[160:163], v[168:171], v[212:215]
	v_mfma_f32_16x16x32_bf16 v[216:219], v[160:163], v[180:183], v[216:219]
	v_mfma_f32_16x16x32_bf16 v[220:223], v[160:163], v[184:187], v[220:223]
	v_mfma_f32_16x16x32_bf16 v[224:227], v[172:175], v[164:167], v[224:227]
	v_mfma_f32_16x16x32_bf16 v[228:231], v[172:175], v[168:171], v[228:231]
	v_mfma_f32_16x16x32_bf16 v[232:235], v[172:175], v[180:183], v[232:235]
	v_mfma_f32_16x16x32_bf16 v[236:239], v[172:175], v[184:187], v[236:239]
	v_mfma_f32_16x16x32_bf16 v[240:243], v[176:179], v[164:167], v[240:243]
	v_mfma_f32_16x16x32_bf16 v[244:247], v[176:179], v[168:171], v[244:247]
	v_mfma_f32_16x16x32_bf16 v[248:251], v[176:179], v[180:183], v[248:251]
	v_mfma_f32_16x16x32_bf16 v[252:255], v[176:179], v[184:187], v[252:255]
	s_mov_b32 s41, s52
	s_mov_b32 s100, s53
	s_mov_b32 s52, s55
	s_mov_b32 s53, s56
	s_mov_b32 s55, s100
	s_mov_b32 s100, s54
	s_mov_b32 s54, s41
	s_mov_b32 s56, s100
	s_add_u32 s38, s38, 0x80
	s_addc_u32 s39, s39, 0
	s_add_u32 s58, s58, 0x80
	s_addc_u32 s59, s59, 0
	v_add3_u32 v124, v85, v87, s52
	v_add3_u32 v125, v86, v87, s53
	ds_read_b128 v[156:159], v124
	ds_read_b128 v[160:163], v124 offset:2048
	ds_read_b128 v[172:175], v124 offset:4096
	ds_read_b128 v[176:179], v124 offset:6144
	ds_read_b128 v[164:167], v125
	ds_read_b128 v[168:171], v125 offset:2048
	ds_read_b128 v[180:183], v125 offset:4096
	ds_read_b128 v[184:187], v125 offset:6144
	s_waitcnt lgkmcnt(8)
	v_mfma_f32_16x16x32_bf16 v[76:79], v[106:109], v[132:135], v[76:79]
	v_mfma_f32_16x16x32_bf16 v[72:75], v[106:109], v[136:139], v[72:75]
	v_mfma_f32_16x16x32_bf16 v[68:71], v[106:109], v[148:151], v[68:71]
	v_mfma_f32_16x16x32_bf16 v[64:67], v[106:109], v[152:155], v[64:67]
	v_mfma_f32_16x16x32_bf16 v[60:63], v[110:113], v[132:135], v[60:63]
	v_mfma_f32_16x16x32_bf16 v[56:59], v[110:113], v[136:139], v[56:59]
	v_mfma_f32_16x16x32_bf16 v[52:55], v[110:113], v[148:151], v[52:55]
	v_mfma_f32_16x16x32_bf16 v[48:51], v[110:113], v[152:155], v[48:51]
	v_mfma_f32_16x16x32_bf16 v[44:47], v[140:143], v[132:135], v[44:47]
	v_mfma_f32_16x16x32_bf16 v[40:43], v[140:143], v[136:139], v[40:43]
	v_mfma_f32_16x16x32_bf16 v[36:39], v[140:143], v[148:151], v[36:39]
	v_mfma_f32_16x16x32_bf16 v[28:31], v[140:143], v[152:155], v[28:31]
	v_mfma_f32_16x16x32_bf16 v[24:27], v[144:147], v[132:135], v[24:27]
	v_mfma_f32_16x16x32_bf16 v[20:23], v[144:147], v[136:139], v[20:23]
	v_mfma_f32_16x16x32_bf16 v[12:15], v[144:147], v[148:151], v[12:15]
	v_mfma_f32_16x16x32_bf16 v[32:35], v[144:147], v[152:155], v[32:35]
	s_waitcnt vmcnt(0) lgkmcnt(0)
	s_barrier
; DEVINL f32x4 mfma16(bf16x8 a, bf16x8 b, f32x4 c) { return __builtin_amdgcn_mfma_f32_16x16x32_bf16(a, b, c, 0, 0, 0); }
; DEVINL int ridx(int r) { return ((r >> 4) << 5) | (r & 15); }
; DEVINL void gemm_loop(f32x4 (&acc)[4][4], const u16* __restrict__ A, int lda, const u16* __restrict__ Bt, int ldb,
;                       int m0, int n0, int k0, int nk, char* smem) {
;     ...
;     for (int ks = 0; ks < 2; ++ks)
; #pragma unroll
;       for (int f = 0; f < 4; ++f) {
;         int ra = wr * 64 + f * 16 + fr, rb = wc * 64 + f * 16 + fr;
;         int ch = ks * 4 + fq;
;         af[ks][f] = *(const bf16x8*)(cur + ra * 128 + ((ch ^ ((ra >> 1) & 7)) << 4));
;         bfr[ks][f] = *(const bf16x8*)(cur + 16384 + rb * 128 + ((ch ^ ((rb >> 1) & 7)) << 4));
;       }
;     __builtin_amdgcn_sched_barrier(0);
; #pragma unroll
;     for (int ks = 0; ks < 2; ++ks)
; #pragma unroll
;       for (int mf = 0; mf < 4; ++mf)
; #pragma unroll
;         for (int nf = 0; nf < 4; ++nf) acc[mf][nf] = mfma16(af[ks][mf], bfr[ks][nf], acc[mf][nf]);
; DEVINL void p6_tile(const Params& p, char* smem, int mt, int nt) {
;     ...
; #pragma unroll
;   for (int mf = 0; mf < 4; ++mf) {
;     const int rb = m0 + wr * 64 + mf * 16 + (lane >> 4) * 4;
;     float rs[4];
; #pragma unroll
;     for (int j = 0; j < 4; ++j) rs[j] = rstd1[ridx(rb) + j];
	v_add3_u32 v125, v86, v88, s54
	ds_read_b128 v[132:135], v125
	ds_read_b128 v[136:139], v125 offset:2048
	ds_read_b128 v[148:151], v125 offset:4096
	ds_read_b128 v[152:155], v125 offset:6144
	v_mfma_f32_16x16x32_bf16 v[76:79], v[156:159], v[164:167], v[76:79]
	v_mfma_f32_16x16x32_bf16 v[72:75], v[156:159], v[168:171], v[72:75]
	v_mfma_f32_16x16x32_bf16 v[68:71], v[156:159], v[180:183], v[68:71]
	v_mfma_f32_16x16x32_bf16 v[64:67], v[156:159], v[184:187], v[64:67]
	v_mfma_f32_16x16x32_bf16 v[60:63], v[160:163], v[164:167], v[60:63]
	v_mfma_f32_16x16x32_bf16 v[56:59], v[160:163], v[168:171], v[56:59]
	v_mfma_f32_16x16x32_bf16 v[52:55], v[160:163], v[180:183], v[52:55]
	v_mfma_f32_16x16x32_bf16 v[48:51], v[160:163], v[184:187], v[48:51]
	v_mfma_f32_16x16x32_bf16 v[44:47], v[172:175], v[164:167], v[44:47]
	v_mfma_f32_16x16x32_bf16 v[40:43], v[172:175], v[168:171], v[40:43]
	v_mfma_f32_16x16x32_bf16 v[36:39], v[172:175], v[180:183], v[36:39]
	v_mfma_f32_16x16x32_bf16 v[28:31], v[172:175], v[184:187], v[28:31]
	v_mfma_f32_16x16x32_bf16 v[24:27], v[176:179], v[164:167], v[24:27]
	v_mfma_f32_16x16x32_bf16 v[20:23], v[176:179], v[168:171], v[20:23]
	v_mfma_f32_16x16x32_bf16 v[12:15], v[176:179], v[180:183], v[12:15]
	v_mfma_f32_16x16x32_bf16 v[32:35], v[176:179], v[184:187], v[32:35]
	s_waitcnt lgkmcnt(0)
	v_add3_u32 v125, v86, v87, s54
	ds_read_b128 v[164:167], v125
	ds_read_b128 v[168:171], v125 offset:2048
	ds_read_b128 v[180:183], v125 offset:4096
	ds_read_b128 v[184:187], v125 offset:6144
	v_mfma_f32_16x16x32_bf16 v[188:191], v[106:109], v[132:135], v[188:191]
	v_mfma_f32_16x16x32_bf16 v[196:199], v[106:109], v[136:139], v[196:199]
	v_mfma_f32_16x16x32_bf16 v[200:203], v[106:109], v[148:151], v[200:203]
	v_mfma_f32_16x16x32_bf16 v[204:207], v[106:109], v[152:155], v[204:207]
	v_mfma_f32_16x16x32_bf16 v[208:211], v[110:113], v[132:135], v[208:211]
	v_mfma_f32_16x16x32_bf16 v[212:215], v[110:113], v[136:139], v[212:215]
	v_mfma_f32_16x16x32_bf16 v[216:219], v[110:113], v[148:151], v[216:219]
	v_mfma_f32_16x16x32_bf16 v[220:223], v[110:113], v[152:155], v[220:223]
	v_mfma_f32_16x16x32_bf16 v[224:227], v[140:143], v[132:135], v[224:227]
	v_mfma_f32_16x16x32_bf16 v[228:231], v[140:143], v[136:139], v[228:231]
	v_mfma_f32_16x16x32_bf16 v[232:235], v[140:143], v[148:151], v[232:235]
	v_mfma_f32_16x16x32_bf16 v[236:239], v[140:143], v[152:155], v[236:239]
	v_mfma_f32_16x16x32_bf16 v[240:243], v[144:147], v[132:135], v[240:243]
	v_mfma_f32_16x16x32_bf16 v[244:247], v[144:147], v[136:139], v[244:247]
	v_mfma_f32_16x16x32_bf16 v[248:251], v[144:147], v[148:151], v[248:251]
	v_mfma_f32_16x16x32_bf16 v[252:255], v[144:147], v[152:155], v[252:255]
	s_waitcnt lgkmcnt(0)
	v_mfma_f32_16x16x32_bf16 v[188:191], v[156:159], v[164:167], v[188:191]
	v_mfma_f32_16x16x32_bf16 v[196:199], v[156:159], v[168:171], v[196:199]
	v_mfma_f32_16x16x32_bf16 v[200:203], v[156:159], v[180:183], v[200:203]
	v_mfma_f32_16x16x32_bf16 v[204:207], v[156:159], v[184:187], v[204:207]
	v_mfma_f32_16x16x32_bf16 v[208:211], v[160:163], v[164:167], v[208:211]
	v_mfma_f32_16x16x32_bf16 v[212:215], v[160:163], v[168:171], v[212:215]
	v_mfma_f32_16x16x32_bf16 v[216:219], v[160:163], v[180:183], v[216:219]
	v_mfma_f32_16x16x32_bf16 v[220:223], v[160:163], v[184:187], v[220:223]
	v_mfma_f32_16x16x32_bf16 v[224:227], v[172:175], v[164:167], v[224:227]
	v_mfma_f32_16x16x32_bf16 v[228:231], v[172:175], v[168:171], v[228:231]
	v_mfma_f32_16x16x32_bf16 v[232:235], v[172:175], v[180:183], v[232:235]
	v_mfma_f32_16x16x32_bf16 v[236:239], v[172:175], v[184:187], v[236:239]
	v_mfma_f32_16x16x32_bf16 v[240:243], v[176:179], v[164:167], v[240:243]
	v_mfma_f32_16x16x32_bf16 v[244:247], v[176:179], v[168:171], v[244:247]
	v_mfma_f32_16x16x32_bf16 v[248:251], v[176:179], v[180:183], v[248:251]
	v_mfma_f32_16x16x32_bf16 v[252:255], v[176:179], v[184:187], v[252:255]
	s_nop 15
	v_readlane_b32 s52, v195, 0
	v_readlane_b32 s53, v195, 1
	v_readlane_b32 s54, v195, 2
	v_readlane_b32 s55, v195, 3
	v_readlane_b32 s56, v195, 4
	v_readlane_b32 s57, v195, 5
	v_readlane_b32 s58, v195, 6
	v_readlane_b32 s59, v195, 7
	v_mov_b32_e32 v122, 0x4480
	v_mov_b32_e32 v123, 0x380
	v_mov_b32_e32 v124, 0x100
	v_mov_b32_e32 v125, 0x110
	v_lshrrev_b32_e32 v154, 7, v0
	v_lshl_add_u32 v154, v154, 6, v105
	v_bfe_u32 v155, v0, 4, 2
	v_lshlrev_b32_e32 v156, 3, v154
	v_lshl_add_u32 v156, v155, 4, v156
	v_mov_b32_e32 v157, 0
	v_readlane_b32 s40, v194, 13
	v_readlane_b32 s41, v194, 14
	v_lshl_add_u32 v154, v155, 2, v154
	v_and_b32_e32 v158, 1, v0
	v_lshl_add_u32 v154, v158, 1, v154
	v_lshl_add_u64 v[152:153], v[156:157], 0, s[40:41]
	global_load_dwordx4 v[132:135], v[152:153], off
	global_load_dwordx4 v[136:139], v[152:153], off offset:128
	global_load_dwordx4 v[140:143], v[152:153], off offset:256
	global_load_dwordx4 v[144:147], v[152:153], off offset:384
	v_mul_lo_u32 v159, v154, s24
	v_lshlrev_b32_e32 v160, 7, v102
	v_bfe_u32 v161, v0, 6, 1
	v_lshl_add_u32 v160, v161, 6, v160
	v_and_b32_e32 v161, 14, v0
	v_lshl_add_u32 v160, v161, 1, v160
	v_add_u32_e32 v156, v159, v160
	v_cmp_eq_u32_e32 vcc, 0, v158
	v_lshl_add_u64 v[148:149], v[156:157], 0, s[84:85]
	s_mov_b32 s38, 0x1600
	s_mov_b32 s39, 0
	v_lshl_add_u64 v[150:151], v[148:149], 0, s[38:39]
	s_mov_b32 s38, 0x16000
	s_waitcnt vmcnt(0)
; DEVINL float lane_xor1(float v) { return dpp_f<0xB1>(v); }
; DEVINL void store_pairs(u16* base, size_t ld, int rb, int col, float v0, float v1, float v2, float v3) {
;   const float p0 = lane_xor1(v0), p1 = lane_xor1(v1), p2 = lane_xor1(v2), p3 = lane_xor1(v3);
;   const bool odd = (col & 1) != 0;
;   const int r0 = odd ? rb + 2 : rb, c0 = col & ~1;
;   const unsigned w0 = odd ? pack2(p2, v2) : pack2(v0, p0);
;   const unsigned w1 = odd ? pack2(p3, v3) : pack2(v1, p1);
;   *(unsigned*)(base + (size_t)r0 * ld + c0) = w0;
;   *(unsigned*)(base + (size_t)(r0 + 1) * ld + c0) = w1;
; }
; DEVINL float sigmoidf_(float x) { return __builtin_amdgcn_rcpf(1.f + __expf(-x)); }
; DEVINL float siluf_(float x) { return x * __builtin_amdgcn_rcpf(1.f + __expf(-x)); }
; DEVINL void p6_tile(const Params& p, char* smem, int mt, int nt) {
;     ...
;     for (int nf = 0; nf < 2; ++nf) {
;       const int hid = nt * 64 + wc * 32 + nf * 16 + (lane & 15);
;       float a[4];
; #pragma unroll
;       for (int j = 0; j < 4; ++j) {
;         float g = acc[mf][nf][j] * rs[j], u = acc[mf][nf + 2][j] * rs[j];
;         a[j] = siluf_(g) * u;
;       }
;       store_pairs(actb, DFF, rb, hid, a[0], a[1], a[2], a[3]);
;     }
	v_mul_f32_e32 v162, v76, v132
	v_mul_f32_e32 v163, v77, v133
	v_mul_f32_e32 v164, v78, v134
	v_mul_f32_e32 v165, v79, v135
	v_mul_f32_e32 v166, v68, v132
	v_mul_f32_e32 v167, v69, v133
	v_mul_f32_e32 v168, v70, v134
	v_mul_f32_e32 v169, v71, v135
	v_mul_f32_e32 v170, 0xbfb8aa3b, v162
	v_mul_f32_e32 v171, 0xbfb8aa3b, v163
	v_mul_f32_e32 v172, 0xbfb8aa3b, v164
	v_mul_f32_e32 v173, 0xbfb8aa3b, v165
	v_exp_f32_e32 v170, v170
	v_exp_f32_e32 v171, v171
	v_exp_f32_e32 v172, v172
	v_exp_f32_e32 v173, v173
	v_add_f32_e32 v170, 1.0, v170
	v_add_f32_e32 v171, 1.0, v171
	v_add_f32_e32 v172, 1.0, v172
	v_add_f32_e32 v173, 1.0, v173
	v_rcp_f32_e32 v170, v170
	v_rcp_f32_e32 v171, v171
	v_rcp_f32_e32 v172, v172
	v_rcp_f32_e32 v173, v173
	v_mul_f32_e32 v162, v162, v170
	v_mul_f32_e32 v163, v163, v171
	v_mul_f32_e32 v164, v164, v172
	v_mul_f32_e32 v165, v165, v173
	v_mul_f32_e32 v166, v166, v162
	v_mul_f32_e32 v167, v167, v163
	v_mul_f32_e32 v168, v168, v164
	v_mul_f32_e32 v169, v169, v165
	v_add_u32_e32 v166, 0x8000, v166
	v_add_u32_e32 v167, 0x8000, v167
	v_add_u32_e32 v168, 0x8000, v168
	v_add_u32_e32 v169, 0x8000, v169
	s_nop 1
	v_mov_b32_dpp v174, v166 quad_perm:[1,0,3,2] row_mask:0xf bank_mask:0xf bound_ctrl:1
	v_mov_b32_dpp v175, v167 quad_perm:[1,0,3,2] row_mask:0xf bank_mask:0xf bound_ctrl:1
	v_mov_b32_dpp v176, v168 quad_perm:[1,0,3,2] row_mask:0xf bank_mask:0xf bound_ctrl:1
	v_mov_b32_dpp v177, v169 quad_perm:[1,0,3,2] row_mask:0xf bank_mask:0xf bound_ctrl:1
	v_cndmask_b32_e32 v178, v176, v166, vcc
	v_cndmask_b32_e32 v179, v168, v174, vcc
	v_cndmask_b32_e32 v180, v177, v167, vcc
	v_cndmask_b32_e32 v181, v169, v175, vcc
	v_perm_b32 v178, v179, v178, s25
	v_perm_b32 v180, v181, v180, s25
	global_store_dword v[148:149], v178, off
	global_store_dword v[150:151], v180, off
	v_mul_f32_e32 v162, v72, v132
	v_mul_f32_e32 v163, v73, v133
	v_mul_f32_e32 v164, v74, v134
	v_mul_f32_e32 v165, v75, v135
	v_mul_f32_e32 v166, v64, v132
	v_mul_f32_e32 v167, v65, v133
	v_mul_f32_e32 v168, v66, v134
	v_mul_f32_e32 v169, v67, v135
	v_mul_f32_e32 v170, 0xbfb8aa3b, v162
	v_mul_f32_e32 v171, 0xbfb8aa3b, v163
	v_mul_f32_e32 v172, 0xbfb8aa3b, v164
	v_mul_f32_e32 v173, 0xbfb8aa3b, v165
	v_exp_f32_e32 v170, v170
	v_exp_f32_e32 v171, v171
	v_exp_f32_e32 v172, v172
	v_exp_f32_e32 v173, v173
	v_add_f32_e32 v170, 1.0, v170
	v_add_f32_e32 v171, 1.0, v171
	v_add_f32_e32 v172, 1.0, v172
	v_add_f32_e32 v173, 1.0, v173
	v_rcp_f32_e32 v170, v170
	v_rcp_f32_e32 v171, v171
	v_rcp_f32_e32 v172, v172
	v_rcp_f32_e32 v173, v173
	v_mul_f32_e32 v162, v162, v170
	v_mul_f32_e32 v163, v163, v171
	v_mul_f32_e32 v164, v164, v172
	v_mul_f32_e32 v165, v165, v173
	v_mul_f32_e32 v166, v166, v162
	v_mul_f32_e32 v167, v167, v163
	v_mul_f32_e32 v168, v168, v164
	v_mul_f32_e32 v169, v169, v165
	v_add_u32_e32 v166, 0x8000, v166
	v_add_u32_e32 v167, 0x8000, v167
	v_add_u32_e32 v168, 0x8000, v168
	v_add_u32_e32 v169, 0x8000, v169
	s_nop 1
	v_mov_b32_dpp v174, v166 quad_perm:[1,0,3,2] row_mask:0xf bank_mask:0xf bound_ctrl:1
	v_mov_b32_dpp v175, v167 quad_perm:[1,0,3,2] row_mask:0xf bank_mask:0xf bound_ctrl:1
	v_mov_b32_dpp v176, v168 quad_perm:[1,0,3,2] row_mask:0xf bank_mask:0xf bound_ctrl:1
	v_mov_b32_dpp v177, v169 quad_perm:[1,0,3,2] row_mask:0xf bank_mask:0xf bound_ctrl:1
	v_cndmask_b32_e32 v178, v176, v166, vcc
	v_cndmask_b32_e32 v179, v168, v174, vcc
	v_cndmask_b32_e32 v180, v177, v167, vcc
	v_cndmask_b32_e32 v181, v169, v175, vcc
	v_perm_b32 v178, v179, v178, s25
	v_perm_b32 v180, v181, v180, s25
	global_store_dword v[148:149], v178, off offset:32
	global_store_dword v[150:151], v180, off offset:32
	v_mul_f32_e32 v162, v188, v132
	v_mul_f32_e32 v163, v189, v133
	v_mul_f32_e32 v164, v190, v134
	v_mul_f32_e32 v165, v191, v135
	v_mul_f32_e32 v166, v200, v132
	v_mul_f32_e32 v167, v201, v133
	v_mul_f32_e32 v168, v202, v134
	v_mul_f32_e32 v169, v203, v135
	v_mul_f32_e32 v170, 0xbfb8aa3b, v162
	v_mul_f32_e32 v171, 0xbfb8aa3b, v163
	v_mul_f32_e32 v172, 0xbfb8aa3b, v164
	v_mul_f32_e32 v173, 0xbfb8aa3b, v165
	v_exp_f32_e32 v170, v170
	v_exp_f32_e32 v171, v171
	v_exp_f32_e32 v172, v172
	v_exp_f32_e32 v173, v173
	v_add_f32_e32 v170, 1.0, v170
	v_add_f32_e32 v171, 1.0, v171
	v_add_f32_e32 v172, 1.0, v172
	v_add_f32_e32 v173, 1.0, v173
	v_rcp_f32_e32 v170, v170
	v_rcp_f32_e32 v171, v171
	v_rcp_f32_e32 v172, v172
	v_rcp_f32_e32 v173, v173
	v_mul_f32_e32 v162, v162, v170
	v_mul_f32_e32 v163, v163, v171
	v_mul_f32_e32 v164, v164, v172
	v_mul_f32_e32 v165, v165, v173
	v_mul_f32_e32 v166, v166, v162
	v_mul_f32_e32 v167, v167, v163
	v_mul_f32_e32 v168, v168, v164
	v_mul_f32_e32 v169, v169, v165
	v_add_u32_e32 v166, 0x8000, v166
	v_add_u32_e32 v167, 0x8000, v167
	v_add_u32_e32 v168, 0x8000, v168
	v_add_u32_e32 v169, 0x8000, v169
	s_nop 1
	v_mov_b32_dpp v174, v166 quad_perm:[1,0,3,2] row_mask:0xf bank_mask:0xf bound_ctrl:1
	v_mov_b32_dpp v175, v167 quad_perm:[1,0,3,2] row_mask:0xf bank_mask:0xf bound_ctrl:1
	v_mov_b32_dpp v176, v168 quad_perm:[1,0,3,2] row_mask:0xf bank_mask:0xf bound_ctrl:1
	v_mov_b32_dpp v177, v169 quad_perm:[1,0,3,2] row_mask:0xf bank_mask:0xf bound_ctrl:1
	v_cndmask_b32_e32 v178, v176, v166, vcc
	v_cndmask_b32_e32 v179, v168, v174, vcc
	v_cndmask_b32_e32 v180, v177, v167, vcc
	v_cndmask_b32_e32 v181, v169, v175, vcc
	v_perm_b32 v178, v179, v178, s25
	v_perm_b32 v180, v181, v180, s25
	global_store_dword v[148:149], v178, off offset:128
	global_store_dword v[150:151], v180, off offset:128
	v_mul_f32_e32 v162, v196, v132
	v_mul_f32_e32 v163, v197, v133
	v_mul_f32_e32 v164, v198, v134
	v_mul_f32_e32 v165, v199, v135
	v_mul_f32_e32 v166, v204, v132
	v_mul_f32_e32 v167, v205, v133
	v_mul_f32_e32 v168, v206, v134
; DEVINL float lane_xor1(float v) { return dpp_f<0xB1>(v); }
; DEVINL void store_pairs(u16* base, size_t ld, int rb, int col, float v0, float v1, float v2, float v3) {
;   const float p0 = lane_xor1(v0), p1 = lane_xor1(v1), p2 = lane_xor1(v2), p3 = lane_xor1(v3);
;   const bool odd = (col & 1) != 0;
;   const int r0 = odd ? rb + 2 : rb, c0 = col & ~1;
;   const unsigned w0 = odd ? pack2(p2, v2) : pack2(v0, p0);
;   const unsigned w1 = odd ? pack2(p3, v3) : pack2(v1, p1);
;   *(unsigned*)(base + (size_t)r0 * ld + c0) = w0;
;   *(unsigned*)(base + (size_t)(r0 + 1) * ld + c0) = w1;
; }
; DEVINL float sigmoidf_(float x) { return __builtin_amdgcn_rcpf(1.f + __expf(-x)); }
; DEVINL float siluf_(float x) { return x * __builtin_amdgcn_rcpf(1.f + __expf(-x)); }
; DEVINL void p6_tile(const Params& p, char* smem, int mt, int nt) {
;     ...
;     for (int nf = 0; nf < 2; ++nf) {
;       const int hid = nt * 64 + wc * 32 + nf * 16 + (lane & 15);
;       float a[4];
; #pragma unroll
;       for (int j = 0; j < 4; ++j) {
;         float g = acc[mf][nf][j] * rs[j], u = acc[mf][nf + 2][j] * rs[j];
;         a[j] = siluf_(g) * u;
;       }
;       store_pairs(actb, DFF, rb, hid, a[0], a[1], a[2], a[3]);
;     }
	v_mul_f32_e32 v169, v207, v135
	v_mul_f32_e32 v170, 0xbfb8aa3b, v162
	v_mul_f32_e32 v171, 0xbfb8aa3b, v163
	v_mul_f32_e32 v172, 0xbfb8aa3b, v164
	v_mul_f32_e32 v173, 0xbfb8aa3b, v165
	v_exp_f32_e32 v170, v170
	v_exp_f32_e32 v171, v171
	v_exp_f32_e32 v172, v172
	v_exp_f32_e32 v173, v173
	v_add_f32_e32 v170, 1.0, v170
	v_add_f32_e32 v171, 1.0, v171
	v_add_f32_e32 v172, 1.0, v172
	v_add_f32_e32 v173, 1.0, v173
	v_rcp_f32_e32 v170, v170
	v_rcp_f32_e32 v171, v171
	v_rcp_f32_e32 v172, v172
	v_rcp_f32_e32 v173, v173
	v_mul_f32_e32 v162, v162, v170
	v_mul_f32_e32 v163, v163, v171
	v_mul_f32_e32 v164, v164, v172
	v_mul_f32_e32 v165, v165, v173
	v_mul_f32_e32 v166, v166, v162
	v_mul_f32_e32 v167, v167, v163
	v_mul_f32_e32 v168, v168, v164
	v_mul_f32_e32 v169, v169, v165
	v_add_u32_e32 v166, 0x8000, v166
	v_add_u32_e32 v167, 0x8000, v167
	v_add_u32_e32 v168, 0x8000, v168
	v_add_u32_e32 v169, 0x8000, v169
	s_nop 1
	v_mov_b32_dpp v174, v166 quad_perm:[1,0,3,2] row_mask:0xf bank_mask:0xf bound_ctrl:1
	v_mov_b32_dpp v175, v167 quad_perm:[1,0,3,2] row_mask:0xf bank_mask:0xf bound_ctrl:1
	v_mov_b32_dpp v176, v168 quad_perm:[1,0,3,2] row_mask:0xf bank_mask:0xf bound_ctrl:1
	v_mov_b32_dpp v177, v169 quad_perm:[1,0,3,2] row_mask:0xf bank_mask:0xf bound_ctrl:1
	v_cndmask_b32_e32 v178, v176, v166, vcc
	v_cndmask_b32_e32 v179, v168, v174, vcc
	v_cndmask_b32_e32 v180, v177, v167, vcc
	v_cndmask_b32_e32 v181, v169, v175, vcc
	v_perm_b32 v178, v179, v178, s25
	v_perm_b32 v180, v181, v180, s25
	global_store_dword v[148:149], v178, off offset:160
	global_store_dword v[150:151], v180, off offset:160
	v_lshl_add_u64 v[148:149], v[148:149], 0, s[38:39]
	v_lshl_add_u64 v[150:151], v[150:151], 0, s[38:39]
	v_mul_f32_e32 v162, v60, v136
	v_mul_f32_e32 v163, v61, v137
	v_mul_f32_e32 v164, v62, v138
	v_mul_f32_e32 v165, v63, v139
	v_mul_f32_e32 v166, v52, v136
	v_mul_f32_e32 v167, v53, v137
	v_mul_f32_e32 v168, v54, v138
	v_mul_f32_e32 v169, v55, v139
	v_mul_f32_e32 v170, 0xbfb8aa3b, v162
	v_mul_f32_e32 v171, 0xbfb8aa3b, v163
	v_mul_f32_e32 v172, 0xbfb8aa3b, v164
	v_mul_f32_e32 v173, 0xbfb8aa3b, v165
	v_exp_f32_e32 v170, v170
	v_exp_f32_e32 v171, v171
	v_exp_f32_e32 v172, v172
	v_exp_f32_e32 v173, v173
	v_add_f32_e32 v170, 1.0, v170
	v_add_f32_e32 v171, 1.0, v171
	v_add_f32_e32 v172, 1.0, v172
	v_add_f32_e32 v173, 1.0, v173
	v_rcp_f32_e32 v170, v170
	v_rcp_f32_e32 v171, v171
	v_rcp_f32_e32 v172, v172
	v_rcp_f32_e32 v173, v173
	v_mul_f32_e32 v162, v162, v170
	v_mul_f32_e32 v163, v163, v171
	v_mul_f32_e32 v164, v164, v172
	v_mul_f32_e32 v165, v165, v173
	v_mul_f32_e32 v166, v166, v162
	v_mul_f32_e32 v167, v167, v163
	v_mul_f32_e32 v168, v168, v164
	v_mul_f32_e32 v169, v169, v165
	v_add_u32_e32 v166, 0x8000, v166
	v_add_u32_e32 v167, 0x8000, v167
	v_add_u32_e32 v168, 0x8000, v168
	v_add_u32_e32 v169, 0x8000, v169
	s_nop 1
	v_mov_b32_dpp v174, v166 quad_perm:[1,0,3,2] row_mask:0xf bank_mask:0xf bound_ctrl:1
	v_mov_b32_dpp v175, v167 quad_perm:[1,0,3,2] row_mask:0xf bank_mask:0xf bound_ctrl:1
	v_mov_b32_dpp v176, v168 quad_perm:[1,0,3,2] row_mask:0xf bank_mask:0xf bound_ctrl:1
	v_mov_b32_dpp v177, v169 quad_perm:[1,0,3,2] row_mask:0xf bank_mask:0xf bound_ctrl:1
	v_cndmask_b32_e32 v178, v176, v166, vcc
	v_cndmask_b32_e32 v179, v168, v174, vcc
	v_cndmask_b32_e32 v180, v177, v167, vcc
	v_cndmask_b32_e32 v181, v169, v175, vcc
	v_perm_b32 v178, v179, v178, s25
	v_perm_b32 v180, v181, v180, s25
	global_store_dword v[148:149], v178, off
	global_store_dword v[150:151], v180, off
	v_mul_f32_e32 v162, v56, v136
	v_mul_f32_e32 v163, v57, v137
	v_mul_f32_e32 v164, v58, v138
	v_mul_f32_e32 v165, v59, v139
	v_mul_f32_e32 v166, v48, v136
	v_mul_f32_e32 v167, v49, v137
	v_mul_f32_e32 v168, v50, v138
	v_mul_f32_e32 v169, v51, v139
	v_mul_f32_e32 v170, 0xbfb8aa3b, v162
	v_mul_f32_e32 v171, 0xbfb8aa3b, v163
	v_mul_f32_e32 v172, 0xbfb8aa3b, v164
	v_mul_f32_e32 v173, 0xbfb8aa3b, v165
	v_exp_f32_e32 v170, v170
	v_exp_f32_e32 v171, v171
	v_exp_f32_e32 v172, v172
	v_exp_f32_e32 v173, v173
	v_add_f32_e32 v170, 1.0, v170
	v_add_f32_e32 v171, 1.0, v171
	v_add_f32_e32 v172, 1.0, v172
	v_add_f32_e32 v173, 1.0, v173
	v_rcp_f32_e32 v170, v170
	v_rcp_f32_e32 v171, v171
	v_rcp_f32_e32 v172, v172
	v_rcp_f32_e32 v173, v173
	v_mul_f32_e32 v162, v162, v170
	v_mul_f32_e32 v163, v163, v171
	v_mul_f32_e32 v164, v164, v172
	v_mul_f32_e32 v165, v165, v173
	v_mul_f32_e32 v166, v166, v162
	v_mul_f32_e32 v167, v167, v163
	v_mul_f32_e32 v168, v168, v164
	v_mul_f32_e32 v169, v169, v165
	v_add_u32_e32 v166, 0x8000, v166
	v_add_u32_e32 v167, 0x8000, v167
	v_add_u32_e32 v168, 0x8000, v168
	v_add_u32_e32 v169, 0x8000, v169
	s_nop 1
	v_mov_b32_dpp v174, v166 quad_perm:[1,0,3,2] row_mask:0xf bank_mask:0xf bound_ctrl:1
	v_mov_b32_dpp v175, v167 quad_perm:[1,0,3,2] row_mask:0xf bank_mask:0xf bound_ctrl:1
	v_mov_b32_dpp v176, v168 quad_perm:[1,0,3,2] row_mask:0xf bank_mask:0xf bound_ctrl:1
	v_mov_b32_dpp v177, v169 quad_perm:[1,0,3,2] row_mask:0xf bank_mask:0xf bound_ctrl:1
	v_cndmask_b32_e32 v178, v176, v166, vcc
	v_cndmask_b32_e32 v179, v168, v174, vcc
	v_cndmask_b32_e32 v180, v177, v167, vcc
	v_cndmask_b32_e32 v181, v169, v175, vcc
	v_perm_b32 v178, v179, v178, s25
	v_perm_b32 v180, v181, v180, s25
	global_store_dword v[148:149], v178, off offset:32
	global_store_dword v[150:151], v180, off offset:32
	v_mul_f32_e32 v162, v208, v136
	v_mul_f32_e32 v163, v209, v137
	v_mul_f32_e32 v164, v210, v138
	v_mul_f32_e32 v165, v211, v139
	v_mul_f32_e32 v166, v216, v136
	v_mul_f32_e32 v167, v217, v137
	v_mul_f32_e32 v168, v218, v138
	v_mul_f32_e32 v169, v219, v139
	v_mul_f32_e32 v170, 0xbfb8aa3b, v162
	v_mul_f32_e32 v171, 0xbfb8aa3b, v163
; DEVINL float lane_xor1(float v) { return dpp_f<0xB1>(v); }
; DEVINL void store_pairs(u16* base, size_t ld, int rb, int col, float v0, float v1, float v2, float v3) {
;   const float p0 = lane_xor1(v0), p1 = lane_xor1(v1), p2 = lane_xor1(v2), p3 = lane_xor1(v3);
;   const bool odd = (col & 1) != 0;
;   const int r0 = odd ? rb + 2 : rb, c0 = col & ~1;
;   const unsigned w0 = odd ? pack2(p2, v2) : pack2(v0, p0);
;   const unsigned w1 = odd ? pack2(p3, v3) : pack2(v1, p1);
;   *(unsigned*)(base + (size_t)r0 * ld + c0) = w0;
;   *(unsigned*)(base + (size_t)(r0 + 1) * ld + c0) = w1;
; }
; DEVINL float sigmoidf_(float x) { return __builtin_amdgcn_rcpf(1.f + __expf(-x)); }
; DEVINL float siluf_(float x) { return x * __builtin_amdgcn_rcpf(1.f + __expf(-x)); }
; DEVINL void p6_tile(const Params& p, char* smem, int mt, int nt) {
;     ...
;     for (int nf = 0; nf < 2; ++nf) {
;       const int hid = nt * 64 + wc * 32 + nf * 16 + (lane & 15);
;       float a[4];
; #pragma unroll
;       for (int j = 0; j < 4; ++j) {
;         float g = acc[mf][nf][j] * rs[j], u = acc[mf][nf + 2][j] * rs[j];
;         a[j] = siluf_(g) * u;
;       }
;       store_pairs(actb, DFF, rb, hid, a[0], a[1], a[2], a[3]);
;     }
	v_mul_f32_e32 v172, 0xbfb8aa3b, v164
	v_mul_f32_e32 v173, 0xbfb8aa3b, v165
	v_exp_f32_e32 v170, v170
	v_exp_f32_e32 v171, v171
	v_exp_f32_e32 v172, v172
	v_exp_f32_e32 v173, v173
	v_add_f32_e32 v170, 1.0, v170
	v_add_f32_e32 v171, 1.0, v171
	v_add_f32_e32 v172, 1.0, v172
	v_add_f32_e32 v173, 1.0, v173
	v_rcp_f32_e32 v170, v170
	v_rcp_f32_e32 v171, v171
	v_rcp_f32_e32 v172, v172
	v_rcp_f32_e32 v173, v173
	v_mul_f32_e32 v162, v162, v170
	v_mul_f32_e32 v163, v163, v171
	v_mul_f32_e32 v164, v164, v172
	v_mul_f32_e32 v165, v165, v173
	v_mul_f32_e32 v166, v166, v162
	v_mul_f32_e32 v167, v167, v163
	v_mul_f32_e32 v168, v168, v164
	v_mul_f32_e32 v169, v169, v165
	v_add_u32_e32 v166, 0x8000, v166
	v_add_u32_e32 v167, 0x8000, v167
	v_add_u32_e32 v168, 0x8000, v168
	v_add_u32_e32 v169, 0x8000, v169
	s_nop 1
	v_mov_b32_dpp v174, v166 quad_perm:[1,0,3,2] row_mask:0xf bank_mask:0xf bound_ctrl:1
	v_mov_b32_dpp v175, v167 quad_perm:[1,0,3,2] row_mask:0xf bank_mask:0xf bound_ctrl:1
	v_mov_b32_dpp v176, v168 quad_perm:[1,0,3,2] row_mask:0xf bank_mask:0xf bound_ctrl:1
	v_mov_b32_dpp v177, v169 quad_perm:[1,0,3,2] row_mask:0xf bank_mask:0xf bound_ctrl:1
	v_cndmask_b32_e32 v178, v176, v166, vcc
	v_cndmask_b32_e32 v179, v168, v174, vcc
	v_cndmask_b32_e32 v180, v177, v167, vcc
	v_cndmask_b32_e32 v181, v169, v175, vcc
	v_perm_b32 v178, v179, v178, s25
	v_perm_b32 v180, v181, v180, s25
	global_store_dword v[148:149], v178, off offset:128
	global_store_dword v[150:151], v180, off offset:128
	v_mul_f32_e32 v162, v212, v136
	v_mul_f32_e32 v163, v213, v137
	v_mul_f32_e32 v164, v214, v138
	v_mul_f32_e32 v165, v215, v139
	v_mul_f32_e32 v166, v220, v136
	v_mul_f32_e32 v167, v221, v137
	v_mul_f32_e32 v168, v222, v138
	v_mul_f32_e32 v169, v223, v139
	v_mul_f32_e32 v170, 0xbfb8aa3b, v162
	v_mul_f32_e32 v171, 0xbfb8aa3b, v163
	v_mul_f32_e32 v172, 0xbfb8aa3b, v164
	v_mul_f32_e32 v173, 0xbfb8aa3b, v165
	v_exp_f32_e32 v170, v170
	v_exp_f32_e32 v171, v171
	v_exp_f32_e32 v172, v172
	v_exp_f32_e32 v173, v173
	v_add_f32_e32 v170, 1.0, v170
	v_add_f32_e32 v171, 1.0, v171
	v_add_f32_e32 v172, 1.0, v172
	v_add_f32_e32 v173, 1.0, v173
	v_rcp_f32_e32 v170, v170
	v_rcp_f32_e32 v171, v171
	v_rcp_f32_e32 v172, v172
	v_rcp_f32_e32 v173, v173
	v_mul_f32_e32 v162, v162, v170
	v_mul_f32_e32 v163, v163, v171
	v_mul_f32_e32 v164, v164, v172
	v_mul_f32_e32 v165, v165, v173
	v_mul_f32_e32 v166, v166, v162
	v_mul_f32_e32 v167, v167, v163
	v_mul_f32_e32 v168, v168, v164
	v_mul_f32_e32 v169, v169, v165
	v_add_u32_e32 v166, 0x8000, v166
	v_add_u32_e32 v167, 0x8000, v167
	v_add_u32_e32 v168, 0x8000, v168
	v_add_u32_e32 v169, 0x8000, v169
	s_nop 1
	v_mov_b32_dpp v174, v166 quad_perm:[1,0,3,2] row_mask:0xf bank_mask:0xf bound_ctrl:1
	v_mov_b32_dpp v175, v167 quad_perm:[1,0,3,2] row_mask:0xf bank_mask:0xf bound_ctrl:1
	v_mov_b32_dpp v176, v168 quad_perm:[1,0,3,2] row_mask:0xf bank_mask:0xf bound_ctrl:1
	v_mov_b32_dpp v177, v169 quad_perm:[1,0,3,2] row_mask:0xf bank_mask:0xf bound_ctrl:1
	v_cndmask_b32_e32 v178, v176, v166, vcc
	v_cndmask_b32_e32 v179, v168, v174, vcc
	v_cndmask_b32_e32 v180, v177, v167, vcc
	v_cndmask_b32_e32 v181, v169, v175, vcc
	v_perm_b32 v178, v179, v178, s25
	v_perm_b32 v180, v181, v180, s25
	global_store_dword v[148:149], v178, off offset:160
	global_store_dword v[150:151], v180, off offset:160
	v_lshl_add_u64 v[148:149], v[148:149], 0, s[38:39]
	v_lshl_add_u64 v[150:151], v[150:151], 0, s[38:39]
	v_mul_f32_e32 v162, v44, v140
	v_mul_f32_e32 v163, v45, v141
	v_mul_f32_e32 v164, v46, v142
	v_mul_f32_e32 v165, v47, v143
	v_mul_f32_e32 v166, v36, v140
	v_mul_f32_e32 v167, v37, v141
	v_mul_f32_e32 v168, v38, v142
	v_mul_f32_e32 v169, v39, v143
	v_mul_f32_e32 v170, 0xbfb8aa3b, v162
	v_mul_f32_e32 v171, 0xbfb8aa3b, v163
	v_mul_f32_e32 v172, 0xbfb8aa3b, v164
	v_mul_f32_e32 v173, 0xbfb8aa3b, v165
	v_exp_f32_e32 v170, v170
	v_exp_f32_e32 v171, v171
	v_exp_f32_e32 v172, v172
	v_exp_f32_e32 v173, v173
	v_add_f32_e32 v170, 1.0, v170
	v_add_f32_e32 v171, 1.0, v171
	v_add_f32_e32 v172, 1.0, v172
	v_add_f32_e32 v173, 1.0, v173
	v_rcp_f32_e32 v170, v170
	v_rcp_f32_e32 v171, v171
	v_rcp_f32_e32 v172, v172
	v_rcp_f32_e32 v173, v173
	v_mul_f32_e32 v162, v162, v170
	v_mul_f32_e32 v163, v163, v171
	v_mul_f32_e32 v164, v164, v172
	v_mul_f32_e32 v165, v165, v173
	v_mul_f32_e32 v166, v166, v162
	v_mul_f32_e32 v167, v167, v163
	v_mul_f32_e32 v168, v168, v164
	v_mul_f32_e32 v169, v169, v165
	v_add_u32_e32 v166, 0x8000, v166
	v_add_u32_e32 v167, 0x8000, v167
	v_add_u32_e32 v168, 0x8000, v168
	v_add_u32_e32 v169, 0x8000, v169
	s_nop 1
	v_mov_b32_dpp v174, v166 quad_perm:[1,0,3,2] row_mask:0xf bank_mask:0xf bound_ctrl:1
	v_mov_b32_dpp v175, v167 quad_perm:[1,0,3,2] row_mask:0xf bank_mask:0xf bound_ctrl:1
	v_mov_b32_dpp v176, v168 quad_perm:[1,0,3,2] row_mask:0xf bank_mask:0xf bound_ctrl:1
	v_mov_b32_dpp v177, v169 quad_perm:[1,0,3,2] row_mask:0xf bank_mask:0xf bound_ctrl:1
	v_cndmask_b32_e32 v178, v176, v166, vcc
	v_cndmask_b32_e32 v179, v168, v174, vcc
	v_cndmask_b32_e32 v180, v177, v167, vcc
	v_cndmask_b32_e32 v181, v169, v175, vcc
	v_perm_b32 v178, v179, v178, s25
	v_perm_b32 v180, v181, v180, s25
	global_store_dword v[148:149], v178, off
	global_store_dword v[150:151], v180, off
	v_mul_f32_e32 v162, v40, v140
	v_mul_f32_e32 v163, v41, v141
	v_mul_f32_e32 v164, v42, v142
	v_mul_f32_e32 v165, v43, v143
	v_mul_f32_e32 v166, v28, v140
	v_mul_f32_e32 v167, v29, v141
	v_mul_f32_e32 v168, v30, v142
	v_mul_f32_e32 v169, v31, v143
	v_mul_f32_e32 v170, 0xbfb8aa3b, v162
	v_mul_f32_e32 v171, 0xbfb8aa3b, v163
	v_mul_f32_e32 v172, 0xbfb8aa3b, v164
	v_mul_f32_e32 v173, 0xbfb8aa3b, v165
	v_exp_f32_e32 v170, v170
; DEVINL float lane_xor1(float v) { return dpp_f<0xB1>(v); }
; DEVINL void store_pairs(u16* base, size_t ld, int rb, int col, float v0, float v1, float v2, float v3) {
;   const float p0 = lane_xor1(v0), p1 = lane_xor1(v1), p2 = lane_xor1(v2), p3 = lane_xor1(v3);
;   const bool odd = (col & 1) != 0;
;   const int r0 = odd ? rb + 2 : rb, c0 = col & ~1;
;   const unsigned w0 = odd ? pack2(p2, v2) : pack2(v0, p0);
;   const unsigned w1 = odd ? pack2(p3, v3) : pack2(v1, p1);
;   *(unsigned*)(base + (size_t)r0 * ld + c0) = w0;
;   *(unsigned*)(base + (size_t)(r0 + 1) * ld + c0) = w1;
; }
; DEVINL float sigmoidf_(float x) { return __builtin_amdgcn_rcpf(1.f + __expf(-x)); }
; DEVINL float siluf_(float x) { return x * __builtin_amdgcn_rcpf(1.f + __expf(-x)); }
; DEVINL void p6_tile(const Params& p, char* smem, int mt, int nt) {
;     ...
;     for (int nf = 0; nf < 2; ++nf) {
;       const int hid = nt * 64 + wc * 32 + nf * 16 + (lane & 15);
;       float a[4];
; #pragma unroll
;       for (int j = 0; j < 4; ++j) {
;         float g = acc[mf][nf][j] * rs[j], u = acc[mf][nf + 2][j] * rs[j];
;         a[j] = siluf_(g) * u;
;       }
;       store_pairs(actb, DFF, rb, hid, a[0], a[1], a[2], a[3]);
;     }
	v_exp_f32_e32 v171, v171
	v_exp_f32_e32 v172, v172
	v_exp_f32_e32 v173, v173
	v_add_f32_e32 v170, 1.0, v170
	v_add_f32_e32 v171, 1.0, v171
	v_add_f32_e32 v172, 1.0, v172
	v_add_f32_e32 v173, 1.0, v173
	v_rcp_f32_e32 v170, v170
	v_rcp_f32_e32 v171, v171
	v_rcp_f32_e32 v172, v172
	v_rcp_f32_e32 v173, v173
	v_mul_f32_e32 v162, v162, v170
	v_mul_f32_e32 v163, v163, v171
	v_mul_f32_e32 v164, v164, v172
	v_mul_f32_e32 v165, v165, v173
	v_mul_f32_e32 v166, v166, v162
	v_mul_f32_e32 v167, v167, v163
	v_mul_f32_e32 v168, v168, v164
	v_mul_f32_e32 v169, v169, v165
	v_add_u32_e32 v166, 0x8000, v166
	v_add_u32_e32 v167, 0x8000, v167
	v_add_u32_e32 v168, 0x8000, v168
	v_add_u32_e32 v169, 0x8000, v169
	s_nop 1
	v_mov_b32_dpp v174, v166 quad_perm:[1,0,3,2] row_mask:0xf bank_mask:0xf bound_ctrl:1
	v_mov_b32_dpp v175, v167 quad_perm:[1,0,3,2] row_mask:0xf bank_mask:0xf bound_ctrl:1
	v_mov_b32_dpp v176, v168 quad_perm:[1,0,3,2] row_mask:0xf bank_mask:0xf bound_ctrl:1
	v_mov_b32_dpp v177, v169 quad_perm:[1,0,3,2] row_mask:0xf bank_mask:0xf bound_ctrl:1
	v_cndmask_b32_e32 v178, v176, v166, vcc
	v_cndmask_b32_e32 v179, v168, v174, vcc
	v_cndmask_b32_e32 v180, v177, v167, vcc
	v_cndmask_b32_e32 v181, v169, v175, vcc
	v_perm_b32 v178, v179, v178, s25
	v_perm_b32 v180, v181, v180, s25
	global_store_dword v[148:149], v178, off offset:32
	global_store_dword v[150:151], v180, off offset:32
	v_mul_f32_e32 v162, v224, v140
	v_mul_f32_e32 v163, v225, v141
	v_mul_f32_e32 v164, v226, v142
	v_mul_f32_e32 v165, v227, v143
	v_mul_f32_e32 v166, v232, v140
	v_mul_f32_e32 v167, v233, v141
	v_mul_f32_e32 v168, v234, v142
	v_mul_f32_e32 v169, v235, v143
	v_mul_f32_e32 v170, 0xbfb8aa3b, v162
	v_mul_f32_e32 v171, 0xbfb8aa3b, v163
	v_mul_f32_e32 v172, 0xbfb8aa3b, v164
	v_mul_f32_e32 v173, 0xbfb8aa3b, v165
	v_exp_f32_e32 v170, v170
	v_exp_f32_e32 v171, v171
	v_exp_f32_e32 v172, v172
	v_exp_f32_e32 v173, v173
	v_add_f32_e32 v170, 1.0, v170
	v_add_f32_e32 v171, 1.0, v171
	v_add_f32_e32 v172, 1.0, v172
	v_add_f32_e32 v173, 1.0, v173
	v_rcp_f32_e32 v170, v170
	v_rcp_f32_e32 v171, v171
	v_rcp_f32_e32 v172, v172
	v_rcp_f32_e32 v173, v173
	v_mul_f32_e32 v162, v162, v170
	v_mul_f32_e32 v163, v163, v171
	v_mul_f32_e32 v164, v164, v172
	v_mul_f32_e32 v165, v165, v173
	v_mul_f32_e32 v166, v166, v162
	v_mul_f32_e32 v167, v167, v163
	v_mul_f32_e32 v168, v168, v164
	v_mul_f32_e32 v169, v169, v165
	v_add_u32_e32 v166, 0x8000, v166
	v_add_u32_e32 v167, 0x8000, v167
	v_add_u32_e32 v168, 0x8000, v168
	v_add_u32_e32 v169, 0x8000, v169
	s_nop 1
	v_mov_b32_dpp v174, v166 quad_perm:[1,0,3,2] row_mask:0xf bank_mask:0xf bound_ctrl:1
	v_mov_b32_dpp v175, v167 quad_perm:[1,0,3,2] row_mask:0xf bank_mask:0xf bound_ctrl:1
	v_mov_b32_dpp v176, v168 quad_perm:[1,0,3,2] row_mask:0xf bank_mask:0xf bound_ctrl:1
	v_mov_b32_dpp v177, v169 quad_perm:[1,0,3,2] row_mask:0xf bank_mask:0xf bound_ctrl:1
	v_cndmask_b32_e32 v178, v176, v166, vcc
	v_cndmask_b32_e32 v179, v168, v174, vcc
	v_cndmask_b32_e32 v180, v177, v167, vcc
	v_cndmask_b32_e32 v181, v169, v175, vcc
	v_perm_b32 v178, v179, v178, s25
	v_perm_b32 v180, v181, v180, s25
	global_store_dword v[148:149], v178, off offset:128
	global_store_dword v[150:151], v180, off offset:128
	v_mul_f32_e32 v162, v228, v140
	v_mul_f32_e32 v163, v229, v141
	v_mul_f32_e32 v164, v230, v142
	v_mul_f32_e32 v165, v231, v143
	v_mul_f32_e32 v166, v236, v140
	v_mul_f32_e32 v167, v237, v141
	v_mul_f32_e32 v168, v238, v142
	v_mul_f32_e32 v169, v239, v143
	v_mul_f32_e32 v170, 0xbfb8aa3b, v162
	v_mul_f32_e32 v171, 0xbfb8aa3b, v163
	v_mul_f32_e32 v172, 0xbfb8aa3b, v164
	v_mul_f32_e32 v173, 0xbfb8aa3b, v165
	v_exp_f32_e32 v170, v170
	v_exp_f32_e32 v171, v171
	v_exp_f32_e32 v172, v172
	v_exp_f32_e32 v173, v173
	v_add_f32_e32 v170, 1.0, v170
	v_add_f32_e32 v171, 1.0, v171
	v_add_f32_e32 v172, 1.0, v172
	v_add_f32_e32 v173, 1.0, v173
	v_rcp_f32_e32 v170, v170
	v_rcp_f32_e32 v171, v171
	v_rcp_f32_e32 v172, v172
	v_rcp_f32_e32 v173, v173
	v_mul_f32_e32 v162, v162, v170
	v_mul_f32_e32 v163, v163, v171
	v_mul_f32_e32 v164, v164, v172
	v_mul_f32_e32 v165, v165, v173
	v_mul_f32_e32 v166, v166, v162
	v_mul_f32_e32 v167, v167, v163
	v_mul_f32_e32 v168, v168, v164
	v_mul_f32_e32 v169, v169, v165
	v_add_u32_e32 v166, 0x8000, v166
	v_add_u32_e32 v167, 0x8000, v167
	v_add_u32_e32 v168, 0x8000, v168
	v_add_u32_e32 v169, 0x8000, v169
	s_nop 1
	v_mov_b32_dpp v174, v166 quad_perm:[1,0,3,2] row_mask:0xf bank_mask:0xf bound_ctrl:1
	v_mov_b32_dpp v175, v167 quad_perm:[1,0,3,2] row_mask:0xf bank_mask:0xf bound_ctrl:1
	v_mov_b32_dpp v176, v168 quad_perm:[1,0,3,2] row_mask:0xf bank_mask:0xf bound_ctrl:1
	v_mov_b32_dpp v177, v169 quad_perm:[1,0,3,2] row_mask:0xf bank_mask:0xf bound_ctrl:1
	v_cndmask_b32_e32 v178, v176, v166, vcc
	v_cndmask_b32_e32 v179, v168, v174, vcc
	v_cndmask_b32_e32 v180, v177, v167, vcc
	v_cndmask_b32_e32 v181, v169, v175, vcc
	v_perm_b32 v178, v179, v178, s25
	v_perm_b32 v180, v181, v180, s25
	global_store_dword v[148:149], v178, off offset:160
	global_store_dword v[150:151], v180, off offset:160
	v_lshl_add_u64 v[148:149], v[148:149], 0, s[38:39]
	v_lshl_add_u64 v[150:151], v[150:151], 0, s[38:39]
	v_mul_f32_e32 v162, v24, v144
	v_mul_f32_e32 v163, v25, v145
	v_mul_f32_e32 v164, v26, v146
	v_mul_f32_e32 v165, v27, v147
	v_mul_f32_e32 v166, v12, v144
	v_mul_f32_e32 v167, v13, v145
	v_mul_f32_e32 v168, v14, v146
	v_mul_f32_e32 v169, v15, v147
	v_mul_f32_e32 v170, 0xbfb8aa3b, v162
	v_mul_f32_e32 v171, 0xbfb8aa3b, v163
	v_mul_f32_e32 v172, 0xbfb8aa3b, v164
	v_mul_f32_e32 v173, 0xbfb8aa3b, v165
	v_exp_f32_e32 v170, v170
	v_exp_f32_e32 v171, v171
	v_exp_f32_e32 v172, v172
	v_exp_f32_e32 v173, v173
; DEVINL float siluf_(float x) { return x * __builtin_amdgcn_rcpf(1.f + __expf(-x)); }
; DEVINL void p6_tile(const Params& p, char* smem, int mt, int nt) {
;     ...
;     for (int nf = 0; nf < 2; ++nf) {
;       const int hid = nt * 64 + wc * 32 + nf * 16 + (lane & 15);
;       float a[4];
; #pragma unroll
;       for (int j = 0; j < 4; ++j) {
;         float g = acc[mf][nf][j] * rs[j], u = acc[mf][nf + 2][j] * rs[j];
;         a[j] = siluf_(g) * u;
;       }
;       store_pairs(actb, DFF, rb, hid, a[0], a[1], a[2], a[3]);
;     }
; template <class F>
; DEVINL void gemm_phase(int NT, F&& f) {
;     ...
;   for (int u = u0 + j; u < u1; u += nbx) {
;     const int band = u / (8 * MT), v = u - band * 8 * MT;
;     const int w = min(8, NT - band * 8);
;     f(v / w, band * 8 + v % w);
	v_add_f32_e32 v170, 1.0, v170
	v_add_f32_e32 v171, 1.0, v171
	v_add_f32_e32 v172, 1.0, v172
	v_add_f32_e32 v173, 1.0, v173
	v_rcp_f32_e32 v170, v170
	v_rcp_f32_e32 v171, v171
	v_rcp_f32_e32 v172, v172
	v_rcp_f32_e32 v173, v173
	v_mul_f32_e32 v162, v162, v170
	v_mul_f32_e32 v163, v163, v171
	v_mul_f32_e32 v164, v164, v172
	v_mul_f32_e32 v165, v165, v173
	v_mul_f32_e32 v166, v166, v162
	v_mul_f32_e32 v167, v167, v163
	v_mul_f32_e32 v168, v168, v164
	v_mul_f32_e32 v169, v169, v165
	v_add_u32_e32 v166, 0x8000, v166
	v_add_u32_e32 v167, 0x8000, v167
	v_add_u32_e32 v168, 0x8000, v168
	v_add_u32_e32 v169, 0x8000, v169
	s_nop 1
	v_mov_b32_dpp v174, v166 quad_perm:[1,0,3,2] row_mask:0xf bank_mask:0xf bound_ctrl:1
	v_mov_b32_dpp v175, v167 quad_perm:[1,0,3,2] row_mask:0xf bank_mask:0xf bound_ctrl:1
	v_mov_b32_dpp v176, v168 quad_perm:[1,0,3,2] row_mask:0xf bank_mask:0xf bound_ctrl:1
	v_mov_b32_dpp v177, v169 quad_perm:[1,0,3,2] row_mask:0xf bank_mask:0xf bound_ctrl:1
	v_cndmask_b32_e32 v178, v176, v166, vcc
	v_cndmask_b32_e32 v179, v168, v174, vcc
	v_cndmask_b32_e32 v180, v177, v167, vcc
	v_cndmask_b32_e32 v181, v169, v175, vcc
	v_perm_b32 v178, v179, v178, s25
	v_perm_b32 v180, v181, v180, s25
	global_store_dword v[148:149], v178, off
	global_store_dword v[150:151], v180, off
	v_mul_f32_e32 v162, v20, v144
	v_mul_f32_e32 v163, v21, v145
	v_mul_f32_e32 v164, v22, v146
	v_mul_f32_e32 v165, v23, v147
	v_mul_f32_e32 v166, v32, v144
	v_mul_f32_e32 v167, v33, v145
	v_mul_f32_e32 v168, v34, v146
	v_mul_f32_e32 v169, v35, v147
	v_mul_f32_e32 v170, 0xbfb8aa3b, v162
	v_mul_f32_e32 v171, 0xbfb8aa3b, v163
	v_mul_f32_e32 v172, 0xbfb8aa3b, v164
	v_mul_f32_e32 v173, 0xbfb8aa3b, v165
	v_exp_f32_e32 v170, v170
	v_exp_f32_e32 v171, v171
	v_exp_f32_e32 v172, v172
	v_exp_f32_e32 v173, v173
	v_add_f32_e32 v170, 1.0, v170
	v_add_f32_e32 v171, 1.0, v171
	v_add_f32_e32 v172, 1.0, v172
	v_add_f32_e32 v173, 1.0, v173
	v_rcp_f32_e32 v170, v170
	v_rcp_f32_e32 v171, v171
	v_rcp_f32_e32 v172, v172
	v_rcp_f32_e32 v173, v173
	v_mul_f32_e32 v162, v162, v170
	v_mul_f32_e32 v163, v163, v171
	v_mul_f32_e32 v164, v164, v172
	v_mul_f32_e32 v165, v165, v173
	v_mul_f32_e32 v166, v166, v162
	v_mul_f32_e32 v167, v167, v163
	v_mul_f32_e32 v168, v168, v164
	v_mul_f32_e32 v169, v169, v165
	v_add_u32_e32 v166, 0x8000, v166
	v_add_u32_e32 v167, 0x8000, v167
	v_add_u32_e32 v168, 0x8000, v168
	v_add_u32_e32 v169, 0x8000, v169
	s_nop 1
	v_mov_b32_dpp v174, v166 quad_perm:[1,0,3,2] row_mask:0xf bank_mask:0xf bound_ctrl:1
	v_mov_b32_dpp v175, v167 quad_perm:[1,0,3,2] row_mask:0xf bank_mask:0xf bound_ctrl:1
	v_mov_b32_dpp v176, v168 quad_perm:[1,0,3,2] row_mask:0xf bank_mask:0xf bound_ctrl:1
	v_mov_b32_dpp v177, v169 quad_perm:[1,0,3,2] row_mask:0xf bank_mask:0xf bound_ctrl:1
	v_cndmask_b32_e32 v178, v176, v166, vcc
	v_cndmask_b32_e32 v179, v168, v174, vcc
	v_cndmask_b32_e32 v180, v177, v167, vcc
	v_cndmask_b32_e32 v181, v169, v175, vcc
	v_perm_b32 v178, v179, v178, s25
	v_perm_b32 v180, v181, v180, s25
	global_store_dword v[148:149], v178, off offset:32
	global_store_dword v[150:151], v180, off offset:32
	v_mul_f32_e32 v162, v240, v144
	v_mul_f32_e32 v163, v241, v145
	v_mul_f32_e32 v164, v242, v146
	v_mul_f32_e32 v165, v243, v147
	v_mul_f32_e32 v166, v248, v144
	v_mul_f32_e32 v167, v249, v145
	v_mul_f32_e32 v168, v250, v146
	v_mul_f32_e32 v169, v251, v147
	v_mul_f32_e32 v170, 0xbfb8aa3b, v162
	v_mul_f32_e32 v171, 0xbfb8aa3b, v163
	v_mul_f32_e32 v172, 0xbfb8aa3b, v164
	v_mul_f32_e32 v173, 0xbfb8aa3b, v165
	v_exp_f32_e32 v170, v170
	v_exp_f32_e32 v171, v171
	v_exp_f32_e32 v172, v172
	v_exp_f32_e32 v173, v173
	v_add_f32_e32 v170, 1.0, v170
	v_add_f32_e32 v171, 1.0, v171
	v_add_f32_e32 v172, 1.0, v172
	v_add_f32_e32 v173, 1.0, v173
	v_rcp_f32_e32 v170, v170
	v_rcp_f32_e32 v171, v171
	v_rcp_f32_e32 v172, v172
	v_rcp_f32_e32 v173, v173
	v_mul_f32_e32 v162, v162, v170
	v_mul_f32_e32 v163, v163, v171
	v_mul_f32_e32 v164, v164, v172
	v_mul_f32_e32 v165, v165, v173
	v_mul_f32_e32 v166, v166, v162
	v_mul_f32_e32 v167, v167, v163
	v_mul_f32_e32 v168, v168, v164
	v_mul_f32_e32 v169, v169, v165
	v_add_u32_e32 v166, 0x8000, v166
	v_add_u32_e32 v167, 0x8000, v167
	v_add_u32_e32 v168, 0x8000, v168
	v_add_u32_e32 v169, 0x8000, v169
	s_nop 1
	v_mov_b32_dpp v174, v166 quad_perm:[1,0,3,2] row_mask:0xf bank_mask:0xf bound_ctrl:1
	v_mov_b32_dpp v175, v167 quad_perm:[1,0,3,2] row_mask:0xf bank_mask:0xf bound_ctrl:1
	v_mov_b32_dpp v176, v168 quad_perm:[1,0,3,2] row_mask:0xf bank_mask:0xf bound_ctrl:1
	v_mov_b32_dpp v177, v169 quad_perm:[1,0,3,2] row_mask:0xf bank_mask:0xf bound_ctrl:1
	v_cndmask_b32_e32 v178, v176, v166, vcc
	v_cndmask_b32_e32 v179, v168, v174, vcc
	v_cndmask_b32_e32 v180, v177, v167, vcc
	v_cndmask_b32_e32 v181, v169, v175, vcc
	v_perm_b32 v178, v179, v178, s25
	v_perm_b32 v180, v181, v180, s25
	global_store_dword v[148:149], v178, off offset:128
	global_store_dword v[150:151], v180, off offset:128
	v_mul_f32_e32 v162, v244, v144
	v_mul_f32_e32 v163, v245, v145
	v_mul_f32_e32 v164, v246, v146
	v_mul_f32_e32 v165, v247, v147
	v_mul_f32_e32 v166, v252, v144
	v_mul_f32_e32 v167, v253, v145
	v_mul_f32_e32 v168, v254, v146
	v_mul_f32_e32 v169, v255, v147
	v_mul_f32_e32 v170, 0xbfb8aa3b, v162
	v_mul_f32_e32 v171, 0xbfb8aa3b, v163
	v_mul_f32_e32 v172, 0xbfb8aa3b, v164
	v_mul_f32_e32 v173, 0xbfb8aa3b, v165
	v_exp_f32_e32 v170, v170
	v_exp_f32_e32 v171, v171
	v_exp_f32_e32 v172, v172
	v_exp_f32_e32 v173, v173
	v_add_f32_e32 v170, 1.0, v170
	v_add_f32_e32 v171, 1.0, v171
	v_add_f32_e32 v172, 1.0, v172
	v_add_f32_e32 v173, 1.0, v173
	v_rcp_f32_e32 v170, v170
	v_rcp_f32_e32 v171, v171
	v_rcp_f32_e32 v172, v172
	v_rcp_f32_e32 v173, v173
	v_mul_f32_e32 v162, v162, v170
	v_mul_f32_e32 v163, v163, v171
	v_mul_f32_e32 v164, v164, v172
	v_mul_f32_e32 v165, v165, v173
	v_mul_f32_e32 v166, v166, v162
	v_mul_f32_e32 v167, v167, v163
	v_mul_f32_e32 v168, v168, v164
	v_mul_f32_e32 v169, v169, v165
	v_add_u32_e32 v166, 0x8000, v166
	v_add_u32_e32 v167, 0x8000, v167
	v_add_u32_e32 v168, 0x8000, v168
	v_add_u32_e32 v169, 0x8000, v169
	s_nop 1
	v_mov_b32_dpp v174, v166 quad_perm:[1,0,3,2] row_mask:0xf bank_mask:0xf bound_ctrl:1
	v_mov_b32_dpp v175, v167 quad_perm:[1,0,3,2] row_mask:0xf bank_mask:0xf bound_ctrl:1
	v_mov_b32_dpp v176, v168 quad_perm:[1,0,3,2] row_mask:0xf bank_mask:0xf bound_ctrl:1
	v_mov_b32_dpp v177, v169 quad_perm:[1,0,3,2] row_mask:0xf bank_mask:0xf bound_ctrl:1
	v_cndmask_b32_e32 v178, v176, v166, vcc
	v_cndmask_b32_e32 v179, v168, v174, vcc
	v_cndmask_b32_e32 v180, v177, v167, vcc
	v_cndmask_b32_e32 v181, v169, v175, vcc
	v_perm_b32 v178, v179, v178, s25
	v_perm_b32 v180, v181, v180, s25
	global_store_dword v[148:149], v178, off offset:160
	global_store_dword v[150:151], v180, off offset:160
	v_add_u32_e32 v3, v3, v1
	v_cmp_le_i32_e32 vcc, s0, v3
	s_or_b64 s[36:37], vcc, s[36:37]
	s_andn2_b64 exec, exec, s[36:37]
	s_cbranch_execnz .LBB0_115
	s_or_b64 exec, exec, s[36:37]
